# write-through (sc1) stores on the row phases P1 (U, U8), P5 (A2) and P7 (X1, U fp8) so the seam barriers flush less
# speedup vs baseline: 1.0047x; 1.0047x over previous
.LBB0_218:
	s_add_i32 s0, s20, 0xfffff000
	s_lshr_b32 s1, s0, 11
	s_mulk_i32 s1, 0x3000
	s_add_i32 s4, s1, 0x3000
	s_cmpk_lt_i32 s20, 0x1000
	s_cselect_b32 s1, s21, 0
	s_cselect_b32 s0, s20, s0
	s_cselect_b32 s33, s37, s39
	s_cselect_b32 s62, s36, s38
	s_cselect_b32 s4, 0, s4
	s_lshl_b64 s[0:1], s[0:1], 13
	s_add_u32 s0, s62, s0
	s_addc_u32 s1, s33, s1
	s_lshl_b64 s[62:63], s[4:5], 2
	s_add_u32 s62, s10, s62
	s_addc_u32 s63, s11, s63
	s_add_u32 s68, s62, 0x2000
	v_lshl_add_u64 v[24:25], s[0:1], 0, v[110:111]
	s_addc_u32 s69, s63, 0
	global_load_dwordx4 v[44:47], v110, s[0:1]
	global_load_dwordx4 v[52:55], v110, s[0:1] offset:1024
	global_load_dwordx4 v[20:23], v[116:117], off
	global_load_dwordx4 v[16:19], v[116:117], off offset:1024
	global_load_dwordx4 v[162:165], v129, s[68:69]
	global_load_dwordx4 v[170:173], v183, s[68:69]
	global_load_dwordx4 v[4:7], v129, s[62:63]
	global_load_dwordx4 v[0:3], v129, s[62:63] offset:1024
	global_load_dwordx4 v[56:59], v110, s[0:1] offset:2048
	global_load_dwordx4 v[64:67], v110, s[0:1] offset:3072
	global_load_dwordx4 v[36:39], v[116:117], off offset:2048
	global_load_dwordx4 v[32:35], v[116:117], off offset:3072
	global_load_dwordx4 v[174:177], v186, s[68:69]
	global_load_dwordx4 v[198:201], v187, s[68:69]
	global_load_dwordx4 v[12:15], v129, s[62:63] offset:2048
	global_load_dwordx4 v[8:11], v129, s[62:63] offset:3072
	s_movk_i32 s0, 0x1000
	v_add_co_u32_e64 v48, s[0:1], s0, v24
	s_nop 1
	v_addc_co_u32_e64 v49, s[0:1], 0, v25, s[0:1]
	global_load_dwordx4 v[202:205], v188, s[68:69]
	global_load_dwordx4 v[24:27], v188, s[62:63]
	global_load_dwordx4 v[84:87], v[48:49], off
	global_load_dwordx4 v[80:83], v[48:49], off offset:1024
	global_load_dwordx4 v[68:71], v[118:119], off
	global_load_dwordx4 v[60:63], v[120:121], off
	global_load_dwordx4 v[104:107], v189, s[68:69]
	global_load_dwordx4 v[28:31], v189, s[62:63]
	global_load_dwordx4 v[100:103], v190, s[68:69]
	global_load_dwordx4 v[40:43], v190, s[62:63]
	global_load_dwordx4 v[92:95], v[48:49], off offset:2048
	global_load_dwordx4 v[88:91], v[48:49], off offset:3072
	global_load_dwordx4 v[76:79], v[122:123], off
	global_load_dwordx4 v[72:75], v[124:125], off
	global_load_dwordx4 v[96:99], v191, s[68:69]
	s_nop 0
	global_load_dwordx4 v[48:51], v191, s[62:63]
	s_waitcnt vmcnt(31)
	v_mov_b32_e32 v142, v45
	s_waitcnt vmcnt(30)
	v_mov_b32_e32 v143, v53
	v_mov_b32_e32 v146, v47
	v_mov_b32_e32 v147, v55
	v_mov_b32_e32 v138, v44
	v_mov_b32_e32 v139, v52
	v_mov_b32_e32 v140, v46
	v_mov_b32_e32 v141, v54
	s_waitcnt vmcnt(23)
	v_pk_mul_f32 v[148:149], v[58:59], v[58:59]
	v_pk_mul_f32 v[144:145], v[56:57], v[56:57]
	v_pk_mul_f32 v[142:143], v[142:143], v[142:143]
	v_pk_mul_f32 v[146:147], v[146:147], v[146:147]
	v_pk_add_f32 v[152:153], v[162:163], 1.0 op_sel_hi:[1,0]
	v_pk_add_f32 v[162:163], v[172:173], 1.0 op_sel_hi:[1,0]
	s_waitcnt vmcnt(19)
	v_pk_add_f32 v[172:173], v[174:175], 1.0 op_sel_hi:[1,0]
	s_waitcnt vmcnt(18)
	v_pk_add_f32 v[174:175], v[200:201], 1.0 op_sel_hi:[1,0]
	s_waitcnt vmcnt(15)
	v_pk_add_f32 v[200:201], v[202:203], 1.0 op_sel_hi:[1,0]
	v_pk_mov_b32 v[202:203], v[144:145], v[148:149] op_sel:[1,0]
	v_mov_b32_e32 v145, v149
	v_pk_fma_f32 v[138:139], v[138:139], v[138:139], v[142:143]
	v_pk_fma_f32 v[140:141], v[140:141], v[140:141], v[146:147]
	v_mul_f32_e32 v156, v65, v65
	v_mul_f32_e32 v158, v67, v67
	v_pk_add_f32 v[142:143], v[202:203], v[144:145]
	v_pk_add_f32 v[138:139], v[138:139], v[140:141]
	s_waitcnt vmcnt(13)
	v_mul_f32_e32 v133, v84, v84
	v_mul_f32_e32 v210, v85, v85
	v_mul_f32_e32 v211, v86, v86
	v_mul_f32_e32 v212, v87, v87
	v_pk_add_f32 v[150:151], v[164:165], 1.0 op_sel_hi:[1,0]
	v_pk_add_f32 v[164:165], v[170:171], 1.0 op_sel_hi:[1,0]
	v_pk_add_f32 v[170:171], v[176:177], 1.0 op_sel_hi:[1,0]
	v_pk_add_f32 v[176:177], v[198:199], 1.0 op_sel_hi:[1,0]
	v_pk_add_f32 v[198:199], v[204:205], 1.0 op_sel_hi:[1,0]
	v_pk_fma_f32 v[148:149], v[64:65], v[64:65], v[156:157] op_sel_hi:[1,1,0]
	v_pk_fma_f32 v[204:205], v[66:67], v[66:67], v[158:159] op_sel_hi:[1,1,0]
	v_pk_add_f32 v[140:141], v[142:143], v[142:143] op_sel:[0,1] op_sel_hi:[1,0]
	v_pk_add_f32 v[138:139], v[138:139], v[138:139] op_sel:[0,1] op_sel_hi:[1,0]
	s_waitcnt vmcnt(12)
	v_pk_mul_f32 v[160:161], v[82:83], v[82:83]
	v_pk_mul_f32 v[154:155], v[80:81], v[80:81]
	v_mov_b32_e32 v149, v211
	v_mov_b32_e32 v205, v212
	v_mov_b32_e32 v141, v210
	v_mov_b32_e32 v139, v133
	v_pk_mov_b32 v[206:207], v[154:155], v[160:161] op_sel:[1,0]
	v_mov_b32_e32 v155, v161
	v_pk_add_f32 v[142:143], v[148:149], v[204:205]
	v_pk_add_f32 v[138:139], v[138:139], v[140:141]
	s_waitcnt vmcnt(5)
	v_mul_f32_e32 v166, v93, v93
	v_mul_f32_e32 v168, v95, v95
	v_pk_add_f32 v[144:145], v[206:207], v[154:155]
	v_pk_add_f32 v[138:139], v[138:139], v[142:143]
	s_waitcnt vmcnt(4)
	v_mul_f32_e32 v213, v88, v88
	v_mul_f32_e32 v214, v89, v89
	v_mul_f32_e32 v215, v90, v90
	v_mul_f32_e32 v216, v91, v91
	v_pk_fma_f32 v[160:161], v[92:93], v[92:93], v[166:167] op_sel_hi:[1,1,0]
	v_pk_fma_f32 v[208:209], v[94:95], v[94:95], v[168:169] op_sel_hi:[1,1,0]
	v_pk_add_f32 v[144:145], v[144:145], v[144:145] op_sel:[0,1] op_sel_hi:[1,0]
	v_pk_add_f32 v[138:139], v[138:139], v[138:139] op_sel:[0,1] op_sel_hi:[1,0]
	v_mov_b32_e32 v161, v215
	v_mov_b32_e32 v209, v216
	v_mov_b32_e32 v145, v214
	v_mov_b32_e32 v139, v213
	v_pk_add_f32 v[146:147], v[160:161], v[208:209]
	v_pk_add_f32 v[138:139], v[138:139], v[144:145]
	v_lshl_add_u64 v[178:179], s[28:29], 0, v[136:137]
	v_pk_add_f32 v[138:139], v[138:139], v[146:147]
	v_add_co_u32_e64 v178, s[0:1], s16, v178
	v_add_f32_e32 v133, v138, v139
	ds_bpermute_b32 v138, v109, v133
	v_lshl_add_u64 v[180:181], s[28:29], 0, v[134:135]
	v_addc_co_u32_e64 v179, s[0:1], 0, v179, s[0:1]
	v_add_co_u32_e64 v180, s[0:1], s17, v180
	s_waitcnt lgkmcnt(0)
	v_add_f32_e32 v133, v133, v138
	ds_bpermute_b32 v138, v113, v133
	s_mov_b32 s4, 0x800000
	v_addc_co_u32_e64 v181, s[0:1], 0, v181, s[0:1]
	v_mov_b32_e32 v218, v111
	s_waitcnt lgkmcnt(0)
	v_add_f32_e32 v133, v133, v138
	ds_bpermute_b32 v138, v115, v133
	v_mov_b32_e32 v219, v111
	v_pk_add_f32 v[106:107], v[106:107], 1.0 op_sel_hi:[1,0]
	v_pk_add_f32 v[104:105], v[104:105], 1.0 op_sel_hi:[1,0]
	v_pk_add_f32 v[100:101], v[100:101], 1.0 op_sel_hi:[1,0]
	s_waitcnt lgkmcnt(0)
	v_add_f32_e32 v133, v133, v138
	ds_bpermute_b32 v138, v157, v133
	s_waitcnt vmcnt(1)
	v_pk_add_f32 v[96:97], v[96:97], 1.0 op_sel_hi:[1,0]
	v_mov_b32_e32 v220, v111
	v_mov_b32_e32 v221, v111
	v_mov_b32_e32 v222, v111
	s_waitcnt lgkmcnt(0)
	v_add_f32_e32 v133, v133, v138
	ds_bpermute_b32 v138, v159, v133
	v_mov_b32_e32 v223, v111
	v_mov_b32_e32 v224, v111
	v_mov_b32_e32 v225, v111
	v_add_u32_e32 v217, s7, v169
	s_waitcnt lgkmcnt(0)
	v_add_f32_e32 v133, v133, v138
	ds_bpermute_b32 v138, v167, v133
	s_addk_i32 s7, 0x1010
	s_add_u32 s20, s20, 1
	v_pk_add_f32 v[102:103], v[102:103], 1.0 op_sel_hi:[1,0]
	v_pk_add_f32 v[98:99], v[98:99], 1.0 op_sel_hi:[1,0]
	s_waitcnt lgkmcnt(0)
	v_add_f32_e32 v133, v133, v138
	v_fmamk_f32 v133, v133, 0x3a000000, v192
	v_mul_f32_e32 v138, 0x4b800000, v133
	v_cmp_gt_f32_e64 s[0:1], s4, v133
	s_addc_u32 s21, s21, 0
	v_lshl_add_u64 v[134:135], v[134:135], 0, s[8:9]
	v_cndmask_b32_e64 v133, v133, v138, s[0:1]
	v_rsq_f32_e32 v133, v133
	v_lshl_add_u64 v[136:137], v[136:137], 0, s[12:13]
	s_cmpk_eq_i32 s7, 0x4040
	v_mul_f32_e32 v138, 0x45800000, v133
	v_cndmask_b32_e64 v138, v133, v138, s[0:1]
	v_pk_mul_f32 v[44:45], v[44:45], v[138:139] op_sel_hi:[1,0]
	v_pk_mul_f32 v[52:53], v[52:53], v[138:139] op_sel_hi:[1,0]
	v_pk_mul_f32 v[20:21], v[20:21], v[44:45]
	v_pk_mul_f32 v[16:17], v[16:17], v[52:53]
	v_pk_fma_f32 v[4:5], v[152:153], v[20:21], v[4:5]
	v_pk_mul_f32 v[46:47], v[46:47], v[138:139] op_sel_hi:[1,0]
	v_cvt_pk_fp8_f32 v218, v4, v5
	v_pk_mul_f32 v[54:55], v[54:55], v[138:139] op_sel_hi:[1,0]
	v_pk_mul_f32 v[56:57], v[56:57], v[138:139] op_sel_hi:[1,0]
	v_pk_mul_f32 v[64:65], v[64:65], v[138:139] op_sel_hi:[1,0]
	v_pk_mul_f32 v[86:87], v[86:87], v[138:139] op_sel_hi:[1,0]
	v_pk_mul_f32 v[84:85], v[84:85], v[138:139] op_sel_hi:[1,0]
	v_pk_mul_f32 v[82:83], v[82:83], v[138:139] op_sel_hi:[1,0]
	v_pk_mul_f32 v[80:81], v[80:81], v[138:139] op_sel_hi:[1,0]
	v_pk_mul_f32 v[92:93], v[92:93], v[138:139] op_sel_hi:[1,0]
	v_pk_mul_f32 v[88:89], v[88:89], v[138:139] op_sel_hi:[1,0]
	v_pk_fma_f32 v[0:1], v[164:165], v[16:17], v[0:1]
	v_pk_mul_f32 v[22:23], v[22:23], v[46:47]
	v_pk_mul_f32 v[18:19], v[18:19], v[54:55]
	v_pk_mul_f32 v[36:37], v[36:37], v[56:57]
	v_pk_mul_f32 v[32:33], v[32:33], v[64:65]
	v_pk_mul_f32 v[44:45], v[68:69], v[84:85]
	v_pk_mul_f32 v[46:47], v[70:71], v[86:87]
	v_pk_mul_f32 v[52:53], v[60:61], v[80:81]
	v_pk_mul_f32 v[54:55], v[62:63], v[82:83]
	v_pk_mul_f32 v[56:57], v[76:77], v[92:93]
	v_pk_mul_f32 v[60:61], v[72:73], v[88:89]
	v_cvt_pk_fp8_f32 v219, v0, v1
	v_pk_fma_f32 v[6:7], v[150:151], v[22:23], v[6:7]
	v_pk_fma_f32 v[2:3], v[162:163], v[18:19], v[2:3]
	v_pk_fma_f32 v[12:13], v[172:173], v[36:37], v[12:13]
	v_pk_fma_f32 v[8:9], v[176:177], v[32:33], v[8:9]
	v_pk_fma_f32 v[16:17], v[198:199], v[46:47], v[26:27]
	v_pk_fma_f32 v[18:19], v[200:201], v[44:45], v[24:25]
	v_pk_fma_f32 v[20:21], v[106:107], v[54:55], v[30:31]
	v_pk_fma_f32 v[22:23], v[104:105], v[52:53], v[28:29]
	v_pk_fma_f32 v[26:27], v[100:101], v[56:57], v[40:41]
	s_waitcnt vmcnt(0)
	v_pk_fma_f32 v[30:31], v[96:97], v[60:61], v[48:49]
	v_cvt_pk_fp8_f32 v220, v12, v13
	v_cvt_pk_fp8_f32 v221, v8, v9
	v_cvt_pk_fp8_f32 v222, v18, v19
	v_cvt_pk_fp8_f32 v223, v22, v23
	v_cvt_pk_fp8_f32 v224, v26, v27
	v_cvt_pk_fp8_f32 v225, v30, v31
	v_cvt_pk_fp8_f32 v218, v6, v7 op_sel:[0,0,1]
	v_pk_mul_f32 v[58:59], v[58:59], v[138:139] op_sel_hi:[1,0]
	v_pk_mul_f32 v[66:67], v[66:67], v[138:139] op_sel_hi:[1,0]
	v_pk_mul_f32 v[94:95], v[94:95], v[138:139] op_sel_hi:[1,0]
	v_pk_mul_f32 v[90:91], v[90:91], v[138:139] op_sel_hi:[1,0]
	v_pk_mul_f32 v[38:39], v[38:39], v[58:59]
	v_pk_mul_f32 v[34:35], v[34:35], v[66:67]
	v_pk_mul_f32 v[58:59], v[78:79], v[94:95]
	v_pk_mul_f32 v[62:63], v[74:75], v[90:91]
	v_cvt_pk_fp8_f32 v219, v2, v3 op_sel:[0,0,1]
	v_pk_fma_f32 v[14:15], v[170:171], v[38:39], v[14:15]
	v_pk_fma_f32 v[10:11], v[174:175], v[34:35], v[10:11]
	v_pk_fma_f32 v[24:25], v[102:103], v[58:59], v[42:43]
	v_pk_fma_f32 v[28:29], v[98:99], v[62:63], v[50:51]
	v_cvt_pk_bf16_f32 v32, v4, v5
	v_cvt_pk_bf16_f32 v33, v6, v7
	v_cvt_pk_bf16_f32 v4, v0, v1
	v_cvt_pk_bf16_f32 v5, v2, v3
	v_cvt_pk_bf16_f32 v0, v12, v13
	v_cvt_pk_bf16_f32 v1, v14, v15
	v_cvt_pk_bf16_f32 v12, v8, v9
	v_cvt_pk_bf16_f32 v13, v10, v11
	v_cvt_pk_bf16_f32 v8, v18, v19
	v_cvt_pk_bf16_f32 v9, v16, v17
	v_cvt_pk_bf16_f32 v18, v22, v23
	v_cvt_pk_bf16_f32 v19, v20, v21
	v_cvt_pk_bf16_f32 v22, v26, v27
	v_cvt_pk_bf16_f32 v23, v24, v25
	v_cvt_pk_bf16_f32 v26, v30, v31
	v_cvt_pk_bf16_f32 v27, v28, v29
	global_store_dwordx2 v[178:179], v[32:33], off sc1
	ds_write2st64_b64 v217, v[32:33], v[4:5] offset1:1
	ds_write2st64_b64 v217, v[0:1], v[12:13] offset0:2 offset1:3
	ds_write2st64_b64 v217, v[8:9], v[18:19] offset0:4 offset1:5
	ds_write2st64_b64 v217, v[22:23], v[26:27] offset0:6 offset1:7
	v_cvt_pk_fp8_f32 v220, v14, v15 op_sel:[0,0,1]
	v_cvt_pk_fp8_f32 v221, v10, v11 op_sel:[0,0,1]
	v_cvt_pk_fp8_f32 v222, v16, v17 op_sel:[0,0,1]
	v_cvt_pk_fp8_f32 v223, v20, v21 op_sel:[0,0,1]
	v_cvt_pk_fp8_f32 v224, v24, v25 op_sel:[0,0,1]
	v_cvt_pk_fp8_f32 v225, v28, v29 op_sel:[0,0,1]
	global_store_dword v[180:181], v218, off sc1
	global_store_dwordx2 v[178:179], v[4:5], off offset:512 sc1
	global_store_dword v[180:181], v219, off offset:256 sc1
	global_store_dwordx2 v[178:179], v[0:1], off offset:1024 sc1
	global_store_dword v[180:181], v220, off offset:512 sc1
	global_store_dwordx2 v[178:179], v[12:13], off offset:1536 sc1
	global_store_dword v[180:181], v221, off offset:768 sc1
	global_store_dwordx2 v[178:179], v[8:9], off offset:2048 sc1
	global_store_dword v[180:181], v222, off offset:1024 sc1
	global_store_dwordx2 v[178:179], v[18:19], off offset:2560 sc1
	global_store_dword v[180:181], v223, off offset:1280 sc1
	global_store_dwordx2 v[178:179], v[22:23], off offset:3072 sc1
	global_store_dword v[180:181], v224, off offset:1536 sc1
	global_store_dwordx2 v[178:179], v[26:27], off offset:3584 sc1
	global_store_dword v[180:181], v225, off offset:1792 sc1
	s_cbranch_scc0 .LBB0_218
	v_mov_b32_e32 v0, 0
	s_mov_b32 s4, 0
	v_mov_b32_e32 v24, v128
	v_mov_b64_e32 v[26:27], v[130:131]
	v_mov_b32_e32 v1, v0
	v_mov_b32_e32 v2, v0
	v_mov_b32_e32 v3, v0
	v_mov_b32_e32 v12, v0
	v_mov_b32_e32 v13, v0
	v_mov_b32_e32 v14, v0
	v_mov_b32_e32 v15, v0
	v_mov_b32_e32 v8, v0
	v_mov_b32_e32 v9, v0
	v_mov_b32_e32 v10, v0
	v_mov_b32_e32 v11, v0
	v_mov_b32_e32 v16, v0
	v_mov_b32_e32 v17, v0
	v_mov_b32_e32 v18, v0
	v_mov_b32_e32 v19, v0
	v_mov_b32_e32 v4, v0
	v_mov_b32_e32 v5, v0
	v_mov_b32_e32 v6, v0
	v_mov_b32_e32 v7, v0
	v_mov_b32_e32 v20, v0
	v_mov_b32_e32 v21, v0
	v_mov_b32_e32 v22, v0
	v_mov_b32_e32 v23, v0
	s_waitcnt lgkmcnt(0)
	s_barrier

.LBB0_807:
	s_waitcnt vmcnt(11)
	v_lshlrev_b32_e32 v157, 16, v132
	v_lshlrev_b32_e32 v156, 16, v124
	v_lshlrev_b32_e32 v177, 16, v133
	v_lshlrev_b32_e32 v189, 16, v90
	v_and_b32_e32 v188, 0xffff0000, v90
	v_mov_b32_e32 v90, v157
	v_lshlrev_b32_e32 v176, 16, v125
	v_lshlrev_b32_e32 v183, 16, v89
	v_and_b32_e32 v182, 0xffff0000, v89
	v_lshlrev_b32_e32 v89, 16, v134
	s_waitcnt vmcnt(4)
	v_lshlrev_b32_e32 v195, 16, v136
	v_and_b32_e32 v196, 0xffff0000, v136
	v_lshlrev_b32_e32 v199, 16, v137
	v_and_b32_e32 v200, 0xffff0000, v137
	v_pk_add_f32 v[136:137], v[90:91], v[156:157]
	v_mov_b32_e32 v90, v177
	v_lshlrev_b32_e32 v164, 16, v88
	v_and_b32_e32 v168, 0xffff0000, v88
	v_and_b32_e32 v178, 0xffff0000, v125
	v_lshlrev_b32_e32 v88, 16, v126
	v_and_b32_e32 v125, 0xffff0000, v134
	v_lshlrev_b32_e32 v191, 16, v135
	v_and_b32_e32 v193, 0xffff0000, v135
	v_pk_add_f32 v[134:135], v[90:91], v[176:177]
	v_mov_b32_e32 v90, v89
	v_lshlrev_b32_e32 v187, 16, v130
	v_and_b32_e32 v186, 0xffff0000, v130
	v_lshlrev_b32_e32 v190, 16, v127
	v_and_b32_e32 v192, 0xffff0000, v127
	v_lshlrev_b32_e32 v159, 16, v131
	v_and_b32_e32 v158, 0xffff0000, v131
	v_pk_add_f32 v[130:131], v[90:91], v[88:89]
	v_mov_b32_e32 v88, v191
	v_and_b32_e32 v162, 0xffff0000, v124
	v_and_b32_e32 v124, 0xffff0000, v126
	v_lshlrev_b32_e32 v160, 16, v140
	v_pk_add_f32 v[126:127], v[88:89], v[190:191]
	v_pk_add_f32 v[88:89], v[192:193], v[192:193] op_sel:[1,0] op_sel_hi:[0,1]
	v_mul_f32_e32 v89, 0xbfb8aa3b, v160
	v_exp_f32_e32 v89, v89
	v_pk_add_f32 v[124:125], v[124:125], v[124:125] op_sel:[1,0] op_sel_hi:[0,1]
	v_lshlrev_b32_e32 v165, 16, v128
	v_mov_b32_e32 v90, v165
	v_add_f32_e32 v89, 1.0, v89
	v_div_scale_f32 v125, s[24:25], v89, v89, 1.0
	v_rcp_f32_e32 v127, v125
	v_and_b32_e32 v194, 0xffff0000, v140
	v_pk_add_f32 v[156:157], v[90:91], v[164:165]
	v_and_b32_e32 v179, 0xffff0000, v133
	v_fma_f32 v90, -v125, v127, 1.0
	v_fmac_f32_e32 v127, v90, v127
	v_mul_f32_e32 v90, 0xbfb8aa3b, v194
	v_exp_f32_e32 v90, v90
	v_and_b32_e32 v169, 0xffff0000, v128
	v_lshlrev_b32_e32 v181, 16, v129
	v_and_b32_e32 v180, 0xffff0000, v129
	v_pk_add_f32 v[128:129], v[178:179], v[178:179] op_sel:[1,0] op_sel_hi:[0,1]
	v_and_b32_e32 v163, 0xffff0000, v132
	v_div_scale_f32 v129, vcc, 1.0, v89, 1.0
	v_pk_add_f32 v[132:133], v[162:163], v[162:163] op_sel:[1,0] op_sel_hi:[0,1]
	v_mul_f32_e32 v131, v129, v127
	v_pk_mul_f32 v[166:167], v[132:133], v[132:133]
	v_fma_f32 v133, -v125, v131, v129
	v_add_f32_e32 v90, 1.0, v90
	v_fmac_f32_e32 v131, v133, v127
	v_div_scale_f32 v133, s[24:25], v90, v90, 1.0
	v_rcp_f32_e32 v135, v133
	v_fma_f32 v125, -v125, v131, v129
	v_lshlrev_b32_e32 v197, 16, v141
	v_div_fmas_f32 v125, v125, v127, v131
	v_fma_f32 v127, -v133, v135, 1.0
	v_fmac_f32_e32 v135, v127, v135
	v_mul_f32_e32 v127, 0xbfb8aa3b, v197
	v_exp_f32_e32 v127, v127
	v_div_scale_f32 v129, vcc, 1.0, v90, 1.0
	v_mul_f32_e32 v131, v129, v135
	v_fma_f32 v137, -v133, v131, v129
	v_add_f32_e32 v127, 1.0, v127
	v_lshlrev_b32_e32 v201, 16, v142
	v_and_b32_e32 v202, 0xffff0000, v142
	v_lshlrev_b32_e32 v205, 16, v143
	v_and_b32_e32 v206, 0xffff0000, v143
	v_pk_add_f32 v[142:143], v[168:169], v[168:169] op_sel:[1,0] op_sel_hi:[0,1]
	v_fmac_f32_e32 v131, v137, v135
	v_div_scale_f32 v137, s[24:25], v127, v127, 1.0
	v_rcp_f32_e32 v143, v137
	v_fma_f32 v129, -v133, v131, v129
	v_and_b32_e32 v198, 0xffff0000, v141
	v_div_fmas_f32 v129, v129, v135, v131
	v_fma_f32 v131, -v137, v143, 1.0
	v_fmac_f32_e32 v143, v131, v143
	v_mul_f32_e32 v131, 0xbfb8aa3b, v198
	v_exp_f32_e32 v131, v131
	v_div_scale_f32 v133, vcc, 1.0, v127, 1.0
	v_mul_f32_e32 v135, v133, v143
	v_fma_f32 v157, -v137, v135, v133
	v_add_f32_e32 v131, 1.0, v131
	v_fmac_f32_e32 v135, v157, v143
	v_div_scale_f32 v157, s[24:25], v131, v131, 1.0
	v_rcp_f32_e32 v160, v157
	v_fma_f32 v133, -v137, v135, v133
	v_div_fmas_f32 v133, v133, v143, v135
	v_div_scale_f32 v137, vcc, 1.0, v131, 1.0
	v_fma_f32 v135, -v157, v160, 1.0
	v_fmac_f32_e32 v160, v135, v160
	v_mul_f32_e32 v135, 0xbfb8aa3b, v201
	v_exp_f32_e32 v135, v135
	v_mul_f32_e32 v143, v137, v160
	v_fma_f32 v167, -v157, v143, v137
	v_fmac_f32_e32 v143, v167, v160
	v_add_f32_e32 v135, 1.0, v135
	v_div_scale_f32 v167, s[24:25], v135, v135, 1.0
	v_rcp_f32_e32 v168, v167
	v_fma_f32 v137, -v157, v143, v137
	v_div_fmas_f32 v137, v137, v160, v143
	v_div_scale_f32 v157, vcc, 1.0, v135, 1.0
	v_fma_f32 v143, -v167, v168, 1.0
	v_fmac_f32_e32 v168, v143, v168
	v_mul_f32_e32 v143, 0xbfb8aa3b, v202
	v_exp_f32_e32 v143, v143
	v_mul_f32_e32 v160, v157, v168
	v_fma_f32 v169, -v167, v160, v157
	v_fmac_f32_e32 v160, v169, v168
	v_add_f32_e32 v143, 1.0, v143
	v_div_scale_f32 v169, s[24:25], v143, v143, 1.0
	v_rcp_f32_e32 v176, v169
	v_fma_f32 v157, -v167, v160, v157
	v_mul_f32_e32 v167, 0xbfb8aa3b, v205
	v_exp_f32_e32 v167, v167
	v_div_fmas_f32 v157, v157, v168, v160
	v_fma_f32 v160, -v169, v176, 1.0
	v_fmac_f32_e32 v176, v160, v176
	v_div_scale_f32 v160, vcc, 1.0, v143, 1.0
	v_add_f32_e32 v167, 1.0, v167
	v_mul_f32_e32 v168, v160, v176
	v_div_scale_f32 v178, s[24:25], v167, v167, 1.0
	v_fma_f32 v177, -v169, v168, v160
	v_rcp_f32_e32 v179, v178
	v_fmac_f32_e32 v168, v177, v176
	v_fma_f32 v160, -v169, v168, v160
	v_div_fmas_f32 v176, v160, v176, v168
	v_mul_f32_e32 v168, 0xbfb8aa3b, v206
	v_fma_f32 v160, -v178, v179, 1.0
	v_exp_f32_e32 v168, v168
	v_fmac_f32_e32 v179, v160, v179
	v_div_scale_f32 v160, vcc, 1.0, v167, 1.0
	v_mul_f32_e32 v169, v160, v179
	v_fma_f32 v177, -v178, v169, v160
	v_fmac_f32_e32 v169, v177, v179
	v_add_f32_e32 v177, 1.0, v168
	v_div_scale_f32 v168, s[24:25], v177, v177, 1.0
	v_pk_add_f32 v[140:141], v[182:183], v[180:181]
	v_rcp_f32_e32 v180, v168
	v_fma_f32 v160, -v178, v169, v160
	v_div_fmas_f32 v178, v160, v179, v169
	v_mul_f32_e32 v169, 0xbfb8aa3b, v195
	v_fma_f32 v160, -v168, v180, 1.0
	v_exp_f32_e32 v169, v169
	v_fmac_f32_e32 v180, v160, v180
	v_div_scale_f32 v160, vcc, 1.0, v177, 1.0
	v_mul_f32_e32 v181, v160, v180
	v_fma_f32 v179, -v168, v181, v160
	v_fmac_f32_e32 v181, v179, v180
	v_add_f32_e32 v179, 1.0, v169
	v_div_scale_f32 v169, s[24:25], v179, v179, 1.0
	v_rcp_f32_e32 v182, v169
	v_fma_f32 v160, -v168, v181, v160
	v_mul_f32_e32 v168, 0xbfb8aa3b, v196
	v_div_fmas_f32 v180, v160, v180, v181
	v_fma_f32 v160, -v169, v182, 1.0
	v_exp_f32_e32 v168, v168
	v_fmac_f32_e32 v182, v160, v182
	v_div_scale_f32 v160, vcc, 1.0, v179, 1.0
	v_mul_f32_e32 v183, v160, v182
	v_fma_f32 v181, -v169, v183, v160
	v_fmac_f32_e32 v183, v181, v182
	v_add_f32_e32 v181, 1.0, v168
	v_div_scale_f32 v168, s[24:25], v181, v181, 1.0
	v_lshlrev_b32_e32 v203, 16, v138
	v_and_b32_e32 v204, 0xffff0000, v138
	v_lshlrev_b32_e32 v207, 16, v139
	v_and_b32_e32 v208, 0xffff0000, v139
	v_pk_add_f32 v[138:139], v[188:189], v[186:187]
	v_rcp_f32_e32 v186, v168
	v_fma_f32 v160, -v169, v183, v160
	v_mul_f32_e32 v169, 0xbfb8aa3b, v199
	v_div_fmas_f32 v182, v160, v182, v183
	v_fma_f32 v160, -v168, v186, 1.0
	v_exp_f32_e32 v169, v169
	v_fmac_f32_e32 v186, v160, v186
	v_div_scale_f32 v160, vcc, 1.0, v181, 1.0
	v_mul_f32_e32 v187, v160, v186
	v_fma_f32 v183, -v168, v187, v160
	v_fmac_f32_e32 v187, v183, v186
	v_add_f32_e32 v183, 1.0, v169
	v_div_scale_f32 v169, s[24:25], v183, v183, 1.0
	v_rcp_f32_e32 v188, v169
	v_fma_f32 v160, -v168, v187, v160
	v_mul_f32_e32 v168, 0xbfb8aa3b, v200
	v_div_fmas_f32 v186, v160, v186, v187
	v_fma_f32 v160, -v169, v188, 1.0
	v_exp_f32_e32 v168, v168
	v_fmac_f32_e32 v188, v160, v188
	v_div_scale_f32 v160, vcc, 1.0, v183, 1.0
	v_mul_f32_e32 v189, v160, v188
	v_fma_f32 v187, -v169, v189, v160
	v_fmac_f32_e32 v189, v187, v188
	v_add_f32_e32 v187, 1.0, v168
	v_div_scale_f32 v168, s[24:25], v187, v187, 1.0
	v_rcp_f32_e32 v190, v168
	v_fma_f32 v160, -v169, v189, v160
	v_mul_f32_e32 v169, 0xbfb8aa3b, v203
	v_div_fmas_f32 v188, v160, v188, v189
	v_fma_f32 v160, -v168, v190, 1.0
	v_exp_f32_e32 v169, v169
	v_fmac_f32_e32 v190, v160, v190
	v_div_scale_f32 v160, vcc, 1.0, v187, 1.0
	v_mul_f32_e32 v191, v160, v190
	v_fma_f32 v189, -v168, v191, v160
	v_fmac_f32_e32 v191, v189, v190
	v_add_f32_e32 v189, 1.0, v169
	v_div_scale_f32 v169, s[24:25], v189, v189, 1.0
	v_rcp_f32_e32 v192, v169
	v_fma_f32 v160, -v168, v191, v160
	v_mul_f32_e32 v168, 0xbfb8aa3b, v204
	v_div_fmas_f32 v190, v160, v190, v191
	v_fma_f32 v160, -v169, v192, 1.0
	v_exp_f32_e32 v168, v168
	v_fmac_f32_e32 v192, v160, v192
	v_div_scale_f32 v160, vcc, 1.0, v189, 1.0
	v_mul_f32_e32 v193, v160, v192
	v_fma_f32 v191, -v169, v193, v160
	v_fmac_f32_e32 v193, v191, v192
	v_add_f32_e32 v191, 1.0, v168
	v_div_scale_f32 v168, s[24:25], v191, v191, 1.0
	v_rcp_f32_e32 v194, v168
	v_fma_f32 v160, -v169, v193, v160
	v_mul_f32_e32 v169, 0xbfb8aa3b, v207
	v_div_fmas_f32 v192, v160, v192, v193
	v_fma_f32 v160, -v168, v194, 1.0
	v_exp_f32_e32 v169, v169
	v_fmac_f32_e32 v194, v160, v194
	v_div_scale_f32 v160, vcc, 1.0, v191, 1.0
	v_mul_f32_e32 v195, v160, v194
	v_fma_f32 v193, -v168, v195, v160
	v_fmac_f32_e32 v195, v193, v194
	v_add_f32_e32 v193, 1.0, v169
	v_div_scale_f32 v169, s[24:25], v193, v193, 1.0
	v_rcp_f32_e32 v196, v169
	v_fma_f32 v160, -v168, v195, v160
	v_mul_f32_e32 v168, 0xbfb8aa3b, v208
	v_div_fmas_f32 v194, v160, v194, v195
	v_fma_f32 v160, -v169, v196, 1.0
	v_exp_f32_e32 v168, v168
	v_fmac_f32_e32 v196, v160, v196
	v_div_scale_f32 v160, vcc, 1.0, v193, 1.0
	v_mul_f32_e32 v197, v160, v196
	v_fma_f32 v195, -v169, v197, v160
	v_fmac_f32_e32 v197, v195, v196
	v_add_f32_e32 v195, 1.0, v168
	v_div_scale_f32 v168, s[24:25], v195, v195, 1.0
	v_rcp_f32_e32 v198, v168
	v_fma_f32 v160, -v169, v197, v160
	v_div_fmas_f32 v196, v160, v196, v197
	v_lshlrev_b32_e32 v211, 16, v114
	v_fma_f32 v160, -v168, v198, 1.0
	v_fmac_f32_e32 v198, v160, v198
	v_div_scale_f32 v160, vcc, 1.0, v195, 1.0
	v_mul_f32_e32 v169, v160, v198
	v_fma_f32 v197, -v168, v169, v160
	v_fmac_f32_e32 v169, v197, v198
	v_fma_f32 v160, -v168, v169, v160
	v_lshlrev_b32_e32 v212, 16, v122
	v_and_b32_e32 v122, 0xffff0000, v122
	v_and_b32_e32 v114, 0xffff0000, v114
	v_div_fmas_f32 v197, v160, v198, v169
	v_lshlrev_b32_e32 v168, 16, v120
	v_and_b32_e32 v160, 0xffff0000, v120
	v_lshlrev_b32_e32 v202, 16, v116
	v_and_b32_e32 v203, 0xffff0000, v116
	v_and_b32_e32 v204, 0xffff0000, v108
	v_lshlrev_b32_e32 v169, 16, v121
	v_and_b32_e32 v205, 0xffff0000, v121
	v_lshlrev_b32_e32 v208, 16, v117
	v_and_b32_e32 v209, 0xffff0000, v117
	v_lshlrev_b32_e32 v117, 16, v118
	v_lshlrev_b32_e32 v121, 16, v110
	v_and_b32_e32 v116, 0xffff0000, v118
	v_and_b32_e32 v120, 0xffff0000, v110
	v_lshlrev_b32_e32 v110, 16, v115
	v_lshlrev_b32_e32 v118, 16, v123
	s_waitcnt vmcnt(0)
	v_lshlrev_b32_e32 v215, 16, v102
	v_and_b32_e32 v102, 0xffff0000, v102
	v_add_f32_e32 v114, v122, v114
	v_lshlrev_b32_e32 v199, 16, v108
	v_lshlrev_b32_e32 v207, 16, v109
	v_and_b32_e32 v210, 0xffff0000, v109
	v_lshlrev_b32_e32 v109, 16, v119
	v_and_b32_e32 v108, 0xffff0000, v119
	v_lshlrev_b32_e32 v119, 16, v92
	v_and_b32_e32 v92, 0xffff0000, v92
	v_fmac_f32_e32 v114, v144, v102
	v_add_f32_e32 v110, v118, v110
	v_add_f32_e32 v118, v203, v204
	v_and_b32_e32 v102, 0xffff0000, v104
	v_fmac_f32_e32 v118, v144, v92
	v_mul_f32_e32 v92, 0xbfb8aa3b, v102
	v_exp_f32_e32 v92, v92
	v_and_b32_e32 v123, 0xffff0000, v123
	v_and_b32_e32 v115, 0xffff0000, v115
	v_lshlrev_b32_e32 v216, 16, v103
	v_and_b32_e32 v103, 0xffff0000, v103
	v_add_f32_e32 v115, v123, v115
	v_fmac_f32_e32 v115, v144, v103
	v_add_f32_e32 v103, v202, v199
	v_lshlrev_b32_e32 v123, 16, v96
	v_and_b32_e32 v199, 0xffff0000, v96
	v_add_f32_e32 v96, 1.0, v92
	v_lshlrev_b32_e32 v214, 16, v93
	v_and_b32_e32 v93, 0xffff0000, v93
	v_add_f32_e32 v122, v209, v210
	v_div_scale_f32 v92, s[24:25], v96, v96, v102
	v_fmac_f32_e32 v122, v144, v93
	v_rcp_f32_e32 v93, v92
	v_lshlrev_b32_e32 v203, 16, v97
	v_and_b32_e32 v204, 0xffff0000, v97
	v_and_b32_e32 v198, 0xffff0000, v112
	v_fma_f32 v97, -v92, v93, 1.0
	v_fmac_f32_e32 v93, v97, v93
	v_div_scale_f32 v97, vcc, v102, v96, v102
	v_add_f32_e32 v160, v160, v198
	v_mul_f32_e32 v198, v97, v93
	v_fmac_f32_e32 v103, v144, v119
	v_add_f32_e32 v119, v208, v207
	v_fma_f32 v208, -v92, v198, v97
	v_fmac_f32_e32 v198, v208, v93
	v_and_b32_e32 v202, 0xffff0000, v105
	v_fma_f32 v92, -v92, v198, v97
	v_lshlrev_b32_e32 v105, 16, v105
	v_lshlrev_b32_e32 v104, 16, v104
	v_div_fmas_f32 v97, v92, v93, v198
	v_mul_f32_e32 v92, 0xbfb8aa3b, v104
	v_mul_f32_e32 v93, 0xbfb8aa3b, v105
	v_exp_f32_e32 v92, v92
	v_exp_f32_e32 v93, v93
	v_lshlrev_b32_e32 v200, 16, v112
	v_lshlrev_b32_e32 v201, 16, v113
	v_and_b32_e32 v206, 0xffff0000, v113
	v_lshlrev_b32_e32 v113, 16, v111
	v_and_b32_e32 v112, 0xffff0000, v111
	v_and_b32_e32 v111, 0xffff0000, v100
	v_pk_add_f32 v[92:93], v[92:93], 1.0 op_sel_hi:[1,0]
	v_fmac_f32_e32 v160, v144, v111
	v_div_fixup_f32 v96, v97, v96, v102
	v_div_scale_f32 v102, s[24:25], v93, v93, v105
	v_mul_f32_e32 v198, v160, v96
	v_rcp_f32_e32 v160, v102
	v_and_b32_e32 v213, 0xffff0000, v101
	v_lshlrev_b32_e32 v97, 16, v101
	v_lshlrev_b32_e32 v96, 16, v100
	v_pk_add_f32 v[100:101], v[200:201], v[168:169]
	v_add_f32_e32 v111, v205, v206
	v_pk_fma_f32 v[96:97], v[144:145], v[96:97], v[100:101]
	v_fma_f32 v100, -v102, v160, 1.0
	v_fmac_f32_e32 v160, v100, v160
	v_div_scale_f32 v100, vcc, v105, v93, v105
	v_mul_f32_e32 v101, v100, v160
	v_fma_f32 v168, -v102, v101, v100
	v_fmac_f32_e32 v101, v168, v160
	v_fma_f32 v100, -v102, v101, v100
	v_div_scale_f32 v102, s[24:25], v92, v92, v104
	v_rcp_f32_e32 v168, v102
	v_div_fmas_f32 v100, v100, v160, v101
	v_div_fixup_f32 v93, v100, v93, v105
	v_lshlrev_b32_e32 v206, 16, v106
	v_fma_f32 v100, -v102, v168, 1.0
	v_fmac_f32_e32 v168, v100, v168
	v_div_scale_f32 v100, vcc, v104, v92, v104
	v_mul_f32_e32 v101, v100, v168
	v_fma_f32 v105, -v102, v101, v100
	v_fmac_f32_e32 v101, v105, v168
	v_fma_f32 v100, -v102, v101, v100
	v_mul_f32_e32 v102, 0xbfb8aa3b, v202
	v_exp_f32_e32 v102, v102
	v_div_fmas_f32 v100, v100, v168, v101
	v_div_fixup_f32 v92, v100, v92, v104
	v_pk_mul_f32 v[92:93], v[96:97], v[92:93]
	v_add_f32_e32 v100, 1.0, v102
	v_div_scale_f32 v101, s[24:25], v100, v100, v202
	v_rcp_f32_e32 v102, v101
	v_pk_mul_f32 v[96:97], v[92:93], v[92:93]
	v_mul_f32_e32 v104, 0xbfb8aa3b, v206
	v_fma_f32 v96, v198, v198, v96
	v_add_f32_e32 v168, v97, v96
	v_fma_f32 v96, -v101, v102, 1.0
	v_fmac_f32_e32 v102, v96, v102
	v_div_scale_f32 v96, vcc, v202, v100, v202
	v_exp_f32_e32 v104, v104
	v_mul_f32_e32 v97, v96, v102
	v_fma_f32 v105, -v101, v97, v96
	v_fmac_f32_e32 v97, v105, v102
	v_fma_f32 v96, -v101, v97, v96
	v_add_f32_e32 v101, 1.0, v104
	v_div_scale_f32 v104, s[24:25], v101, v101, v206
	v_rcp_f32_e32 v105, v104
	v_and_b32_e32 v106, 0xffff0000, v106
	v_div_fmas_f32 v96, v96, v102, v97
	v_mul_f32_e32 v102, 0xbfb8aa3b, v106
	v_fma_f32 v97, -v104, v105, 1.0
	v_exp_f32_e32 v102, v102
	v_fmac_f32_e32 v105, v97, v105
	v_div_scale_f32 v97, vcc, v206, v101, v206
	v_fmac_f32_e32 v111, v144, v213
	v_div_fixup_f32 v96, v96, v100, v202
	v_mul_f32_e32 v100, v97, v105
	v_mul_f32_e32 v96, v111, v96
	v_fma_f32 v111, -v104, v100, v97
	v_fmac_f32_e32 v100, v111, v105
	v_add_f32_e32 v102, 1.0, v102
	v_fma_f32 v97, -v104, v100, v97
	v_div_scale_f32 v104, s[24:25], v102, v102, v106
	v_rcp_f32_e32 v111, v104
	v_add_f32_e32 v205, v212, v211
	v_div_fmas_f32 v97, v97, v105, v100
	v_fmac_f32_e32 v205, v144, v215
	v_lshlrev_b32_e32 v207, 16, v107
	v_div_fixup_f32 v97, v97, v101, v206
	v_mul_f32_e32 v100, v205, v97
	v_fma_f32 v97, -v104, v111, 1.0
	v_mul_f32_e32 v105, 0xbfb8aa3b, v207
	v_fmac_f32_e32 v111, v97, v111
	v_div_scale_f32 v97, vcc, v106, v102, v106
	v_exp_f32_e32 v105, v105
	v_mul_f32_e32 v101, v97, v111
	v_fma_f32 v160, -v104, v101, v97
	v_fmac_f32_e32 v101, v160, v111
	v_fma_f32 v97, -v104, v101, v97
	v_add_f32_e32 v104, 1.0, v105
	v_div_scale_f32 v105, s[24:25], v104, v104, v207
	v_rcp_f32_e32 v160, v105
	v_div_fmas_f32 v97, v97, v111, v101
	v_and_b32_e32 v107, 0xffff0000, v107
	v_div_fixup_f32 v97, v97, v102, v106
	v_mul_f32_e32 v102, v114, v97
	v_fma_f32 v97, -v105, v160, 1.0
	v_mul_f32_e32 v106, 0xbfb8aa3b, v107
	v_fmac_f32_e32 v160, v97, v160
	v_div_scale_f32 v97, vcc, v207, v104, v207
	v_exp_f32_e32 v106, v106
	v_mul_f32_e32 v101, v97, v160
	v_fma_f32 v111, -v105, v101, v97
	v_fmac_f32_e32 v101, v111, v160
	v_fma_f32 v97, -v105, v101, v97
	v_add_f32_e32 v105, 1.0, v106
	v_div_scale_f32 v106, s[24:25], v105, v105, v107
	v_rcp_f32_e32 v111, v106
	v_div_fmas_f32 v97, v97, v160, v101
	v_fmac_f32_e32 v110, v144, v216
	v_div_fixup_f32 v97, v97, v104, v207
	v_mul_f32_e32 v104, v110, v97
	v_mul_f32_e32 v110, 0xbfb8aa3b, v123
	v_exp_f32_e32 v110, v110
	v_fma_f32 v97, -v106, v111, 1.0
	v_fmac_f32_e32 v111, v97, v111
	v_div_scale_f32 v97, vcc, v107, v105, v107
	v_mul_f32_e32 v101, v97, v111
	v_fma_f32 v114, -v106, v101, v97
	v_add_f32_e32 v110, 1.0, v110
	v_fmac_f32_e32 v101, v114, v111
	v_div_scale_f32 v114, s[24:25], v110, v110, v123
	v_fma_f32 v97, -v106, v101, v97
	v_rcp_f32_e32 v160, v114
	v_div_fmas_f32 v97, v97, v111, v101
	v_div_fixup_f32 v97, v97, v105, v107
	v_mul_f32_e32 v105, 0xbfb8aa3b, v199
	v_exp_f32_e32 v105, v105
	v_mul_f32_e32 v106, v115, v97
	v_fma_f32 v97, -v114, v160, 1.0
	v_fmac_f32_e32 v160, v97, v160
	v_div_scale_f32 v97, vcc, v123, v110, v123
	v_mul_f32_e32 v101, v97, v160
	v_fma_f32 v107, -v114, v101, v97
	v_add_f32_e32 v105, 1.0, v105
	v_fmac_f32_e32 v101, v107, v160
	v_div_scale_f32 v107, s[24:25], v105, v105, v199
	v_fma_f32 v97, -v114, v101, v97
	v_rcp_f32_e32 v111, v107
	v_div_fmas_f32 v97, v97, v160, v101
	v_div_fixup_f32 v97, v97, v110, v123
	v_mul_f32_e32 v110, v103, v97
	v_mul_f32_e32 v103, 0xbfb8aa3b, v203
	v_fma_f32 v97, -v107, v111, 1.0
	v_exp_f32_e32 v103, v103
	v_fmac_f32_e32 v111, v97, v111
	v_div_scale_f32 v97, vcc, v199, v105, v199
	v_mul_f32_e32 v101, v97, v111
	v_fma_f32 v114, -v107, v101, v97
	v_fmac_f32_e32 v101, v114, v111
	v_add_f32_e32 v103, 1.0, v103
	v_fma_f32 v97, -v107, v101, v97
	v_div_scale_f32 v107, s[24:25], v103, v103, v203
	v_rcp_f32_e32 v115, v107
	v_div_fmas_f32 v97, v97, v111, v101
	v_div_fixup_f32 v97, v97, v105, v199
	v_mul_f32_e32 v105, 0xbfb8aa3b, v204
	v_mul_f32_e32 v114, v118, v97
	v_fma_f32 v97, -v107, v115, 1.0
	v_exp_f32_e32 v105, v105
	v_fmac_f32_e32 v115, v97, v115
	v_div_scale_f32 v97, vcc, v203, v103, v203
	v_mul_f32_e32 v101, v97, v115
	v_fma_f32 v111, -v107, v101, v97
	v_fmac_f32_e32 v101, v111, v115
	v_add_f32_e32 v105, 1.0, v105
	v_fma_f32 v97, -v107, v101, v97
	v_div_scale_f32 v107, s[24:25], v105, v105, v204
	v_rcp_f32_e32 v111, v107
	v_div_fmas_f32 v97, v97, v115, v101
	v_fmac_f32_e32 v119, v144, v214
	v_div_fixup_f32 v97, v97, v103, v203
	v_mul_f32_e32 v118, v119, v97
	v_fma_f32 v97, -v107, v111, 1.0
	v_fmac_f32_e32 v111, v97, v111
	v_div_scale_f32 v97, vcc, v204, v105, v204
	v_mul_f32_e32 v101, v97, v111
	v_fma_f32 v103, -v107, v101, v97
	v_fmac_f32_e32 v101, v103, v111
	v_fma_f32 v97, -v107, v101, v97
	v_div_fmas_f32 v97, v97, v111, v101
	v_and_b32_e32 v101, 0xffff0000, v98
	v_lshlrev_b32_e32 v98, 16, v98
	v_mul_f32_e32 v103, 0xbfb8aa3b, v98
	v_exp_f32_e32 v201, v103
	v_mul_f32_e32 v103, 0xbfb8aa3b, v101
	v_exp_f32_e32 v200, v103
	v_div_fixup_f32 v97, v97, v105, v204
	v_mul_f32_e32 v122, v122, v97
	v_and_b32_e32 v202, 0xffff0000, v94
	v_pk_add_f32 v[200:201], v[200:201], 1.0 op_sel_hi:[1,0]
	v_lshlrev_b32_e32 v203, 16, v94
	v_div_scale_f32 v97, s[24:25], v201, v201, v98
	v_rcp_f32_e32 v103, v97
	v_pk_add_f32 v[116:117], v[120:121], v[116:117]
	v_mov_b32_e32 v169, v166
	v_mov_b32_e32 v111, v126
	v_fma_f32 v94, -v97, v103, 1.0
	v_fmac_f32_e32 v103, v94, v103
	v_div_scale_f32 v94, vcc, v98, v201, v98
	v_mul_f32_e32 v105, v94, v103
	v_fma_f32 v107, -v97, v105, v94
	v_fmac_f32_e32 v105, v107, v103
	v_fma_f32 v94, -v97, v105, v94
	v_div_scale_f32 v97, s[24:25], v200, v200, v101
	v_rcp_f32_e32 v107, v97
	v_div_fmas_f32 v94, v94, v103, v105
	v_div_fixup_f32 v121, v94, v201, v98
	v_mov_b32_e32 v105, v130
	v_fma_f32 v94, -v97, v107, 1.0
	v_fmac_f32_e32 v107, v94, v107
	v_div_scale_f32 v94, vcc, v101, v200, v101
	v_mul_f32_e32 v98, v94, v107
	v_fma_f32 v103, -v97, v98, v94
	v_fmac_f32_e32 v98, v103, v107
	v_fma_f32 v94, -v97, v98, v94
	v_div_fmas_f32 v94, v94, v107, v98
	v_mov_b32_e32 v97, v136
	v_div_fixup_f32 v120, v94, v200, v101
	v_pk_fma_f32 v[168:169], v[96:97], v[96:97], v[168:169]
	v_mov_b32_e32 v101, v134
	v_pk_fma_f32 v[168:169], v[100:101], v[100:101], v[168:169]
	v_mov_b32_e32 v103, v128
	v_pk_fma_f32 v[168:169], v[102:103], v[102:103], v[168:169]
	v_lshlrev_b32_e32 v101, 16, v99
	v_pk_fma_f32 v[168:169], v[104:105], v[104:105], v[168:169]
	v_mov_b32_e32 v107, v124
	v_and_b32_e32 v97, 0xffff0000, v99
	v_mul_f32_e32 v94, 0xbfb8aa3b, v101
	v_pk_fma_f32 v[168:169], v[106:107], v[106:107], v[168:169]
	v_exp_f32_e32 v201, v94
	v_mul_f32_e32 v94, 0xbfb8aa3b, v97
	v_pk_fma_f32 v[116:117], v[144:145], v[202:203], v[116:117]
	v_pk_fma_f32 v[168:169], v[110:111], v[110:111], v[168:169]
	v_mov_b32_e32 v115, v88
	v_exp_f32_e32 v200, v94
	v_pk_mul_f32 v[116:117], v[116:117], v[120:121]
	v_pk_fma_f32 v[168:169], v[114:115], v[114:115], v[168:169]
	v_mov_b32_e32 v119, v156
	v_pk_mul_f32 v[164:165], v[140:141], v[140:141]
	v_pk_mul_f32 v[120:121], v[116:117], v[116:117]
	v_pk_fma_f32 v[168:169], v[118:119], v[118:119], v[168:169]
	v_mov_b32_e32 v123, v142
	v_pk_fma_f32 v[168:169], v[122:123], v[122:123], v[168:169]
	v_mov_b32_e32 v98, v121
	v_mov_b32_e32 v99, v165
	v_pk_add_f32 v[98:99], v[98:99], v[168:169]
	v_pk_add_f32 v[168:169], v[200:201], 1.0 op_sel_hi:[1,0]
	v_and_b32_e32 v94, 0xffff0000, v95
	v_div_scale_f32 v103, s[24:25], v169, v169, v101
	v_rcp_f32_e32 v105, v103
	v_lshlrev_b32_e32 v95, 16, v95
	v_pk_add_f32 v[108:109], v[112:113], v[108:109]
	v_pk_mul_f32 v[162:163], v[138:139], v[138:139]
	v_fma_f32 v107, -v103, v105, 1.0
	v_fmac_f32_e32 v105, v107, v105
	v_div_scale_f32 v107, vcc, v101, v169, v101
	v_pk_fma_f32 v[94:95], v[144:145], v[94:95], v[108:109]
	v_mul_f32_e32 v108, v107, v105
	v_fma_f32 v109, -v103, v108, v107
	v_fmac_f32_e32 v108, v109, v105
	v_fma_f32 v103, -v103, v108, v107
	v_div_scale_f32 v107, s[24:25], v168, v168, v97
	v_rcp_f32_e32 v111, v107
	v_div_fmas_f32 v103, v103, v105, v108
	v_div_fixup_f32 v109, v103, v169, v101
	v_mov_b32_e32 v121, v164
	v_fma_f32 v101, -v107, v111, 1.0
	v_fmac_f32_e32 v111, v101, v111
	v_div_scale_f32 v101, vcc, v97, v168, v97
	v_mul_f32_e32 v103, v101, v111
	v_fma_f32 v105, -v107, v103, v101
	v_fmac_f32_e32 v103, v105, v111
	v_fma_f32 v101, -v107, v103, v101
	v_div_fmas_f32 v101, v101, v111, v103
	v_div_fixup_f32 v108, v101, v168, v97
	v_pk_mul_f32 v[94:95], v[94:95], v[108:109]
	v_pk_add_f32 v[98:99], v[120:121], v[98:99]
	v_pk_mul_f32 v[108:109], v[94:95], v[94:95]
	v_mov_b32_e32 v113, v163
	v_mov_b32_e32 v112, v109
	v_pk_add_f32 v[98:99], v[112:113], v[98:99]
	v_mov_b32_e32 v109, v162
	v_pk_add_f32 v[98:99], v[108:109], v[98:99]
	ds_bpermute_b32 v108, v170, v98
	v_lshlrev_b32_e32 v161, 16, v91
	v_and_b32_e32 v160, 0xffff0000, v91
	v_pk_add_f32 v[112:113], v[160:161], v[158:159]
	v_div_fixup_f32 v97, v129, v90, 1.0
	v_pk_mul_f32 v[120:121], v[112:113], v[112:113]
	v_div_fixup_f32 v89, v125, v89, 1.0
	v_mov_b32_e32 v109, v121
	s_waitcnt lgkmcnt(0)
	v_pk_add_f32 v[98:99], v[98:99], v[108:109]
	ds_bpermute_b32 v108, v171, v98
	v_mov_b32_e32 v109, v120
	v_div_fixup_f32 v111, v182, v179, 1.0
	v_div_fixup_f32 v115, v186, v181, 1.0
	v_div_fixup_f32 v119, v188, v183, 1.0
	s_waitcnt lgkmcnt(0)
	v_pk_add_f32 v[98:99], v[98:99], v[108:109]
	ds_bpermute_b32 v109, v170, v99
	ds_bpermute_b32 v108, v172, v98
	v_div_fixup_f32 v120, v190, v187, 1.0
	v_div_fixup_f32 v107, v176, v143, 1.0
	v_div_fixup_f32 v121, v192, v189, 1.0
	v_div_fixup_f32 v101, v133, v127, 1.0
	s_waitcnt lgkmcnt(0)
	v_pk_add_f32 v[98:99], v[98:99], v[108:109]
	ds_bpermute_b32 v109, v171, v99
	ds_bpermute_b32 v108, v173, v98
	v_div_fixup_f32 v103, v137, v131, 1.0
	v_div_fixup_f32 v123, v197, v195, 1.0
	v_div_fixup_f32 v105, v157, v135, 1.0
	s_waitcnt lgkmcnt(0)
	v_pk_add_f32 v[90:91], v[98:99], v[108:109]
	ds_bpermute_b32 v99, v172, v91
	ds_bpermute_b32 v98, v174, v90
	v_div_fixup_f32 v109, v180, v177, 1.0
	v_div_fixup_f32 v108, v178, v167, 1.0
	s_waitcnt lgkmcnt(0)
	v_pk_add_f32 v[90:91], v[90:91], v[98:99]
	ds_bpermute_b32 v99, v173, v91
	ds_bpermute_b32 v98, v175, v90
	s_waitcnt lgkmcnt(0)
	v_pk_add_f32 v[90:91], v[90:91], v[98:99]
	s_nop 0
	v_pk_fma_f32 v[98:99], v[90:91], s[12:13], v[154:155] op_sel_hi:[1,1,0]
	v_div_fixup_f32 v91, v194, v191, 1.0
	v_mul_f32_e32 v90, 0x4b800000, v99
	v_cmp_gt_f32_e32 vcc, s19, v99
	s_nop 1
	v_cndmask_b32_e32 v90, v99, v90, vcc
	v_rsq_f32_e32 v90, v90
	v_div_fixup_f32 v99, v196, v193, 1.0
	v_mul_f32_e32 v125, 0x45800000, v90
	v_cndmask_b32_e32 v90, v90, v125, vcc
	v_mul_f32_e32 v88, v88, v90
	v_mul_f32_e32 v88, v11, v88
	v_mul_f32_e32 v109, v109, v88
	v_mul_f32_e32 v88, v156, v90
	v_mul_f32_e32 v88, v16, v88
	v_mul_f32_e32 v111, v111, v88
	v_mul_f32_e32 v88, v142, v90
	v_mul_f32_e32 v88, v17, v88
	v_mul_f32_e32 v115, v115, v88
	v_mul_f32_e32 v88, v141, v90
	v_mul_f32_e32 v88, v18, v88
	v_mul_f32_e32 v119, v119, v88
	v_mul_f32_e32 v88, v140, v90
	v_mul_f32_e32 v125, v136, v90
	v_mul_f32_e32 v88, v19, v88
	v_mul_f32_e32 v125, v0, v125
	v_mul_f32_e32 v124, v124, v90
	v_mul_f32_e32 v120, v120, v88
	v_mul_f32_e32 v88, v139, v90
	v_mul_f32_e32 v89, v89, v125
	v_mul_f32_e32 v125, v132, v90
	v_mul_f32_e32 v124, v9, v124
	v_mul_f32_e32 v88, v24, v88
	v_mul_f32_e32 v125, v1, v125
	v_mul_f32_e32 v107, v107, v124
	v_mul_f32_e32 v124, v126, v90
	v_mul_f32_e32 v121, v121, v88
	v_mul_f32_e32 v88, v138, v90
	v_mul_f32_e32 v97, v97, v125
	v_mul_f32_e32 v125, v134, v90
	v_mul_f32_e32 v124, v10, v124
	v_mul_f32_e32 v88, v25, v88
	v_mul_f32_e32 v125, v2, v125
	v_mul_f32_e32 v108, v108, v124
	v_mul_f32_e32 v124, v91, v88
	v_mul_f32_e32 v88, v113, v90
	v_mul_f32_e32 v101, v101, v125
	v_mul_f32_e32 v125, v128, v90
	v_mul_f32_e32 v88, v26, v88
	v_mul_f32_e32 v125, v3, v125
	v_mul_f32_e32 v99, v99, v88
	v_mul_f32_e32 v88, v112, v90
	v_mul_f32_e32 v103, v103, v125
	v_mul_f32_e32 v125, v130, v90
	v_mul_f32_e32 v88, v27, v88
	v_mul_f32_e32 v125, v8, v125
	v_mul_f32_e32 v112, v123, v88
	v_mov_b32_e32 v88, 0
	v_mul_f32_e32 v105, v105, v125
	v_cvt_pk_fp8_f32 v88, v89, v97
	v_mov_b32_e32 v89, 0
	v_mov_b32_e32 v90, 0
	v_mov_b32_e32 v91, 0
	v_cvt_pk_fp8_f32 v89, v105, v107
	v_cvt_pk_fp8_f32 v90, v111, v115
	v_cvt_pk_fp8_f32 v91, v121, v124
	v_mul_f32_e32 v97, 0x4b800000, v98
	v_cmp_gt_f32_e32 vcc, s19, v98
	v_cvt_pk_fp8_f32 v88, v101, v103 op_sel:[0,0,1]
	v_cvt_pk_fp8_f32 v89, v108, v109 op_sel:[0,0,1]
	v_cndmask_b32_e32 v97, v98, v97, vcc
	v_cvt_pk_fp8_f32 v90, v119, v120 op_sel:[0,0,1]
	v_cvt_pk_fp8_f32 v91, v99, v112 op_sel:[0,0,1]
	v_rsq_f32_e32 v97, v97
	v_lshl_add_u64 v[98:99], v[148:149], 0, s[22:23]
	global_store_dwordx4 v[98:99], v[88:91], off sc1
	s_nop 1
	v_mul_f32_e32 v88, 0x45800000, v97
	v_cndmask_b32_e32 v88, v97, v88, vcc
	v_mul_f32_e32 v91, v93, v88
	v_mul_f32_e32 v89, v92, v88
	v_mul_f32_e32 v92, v6, v91
	v_mul_f32_e32 v91, v96, v88
	v_mul_f32_e32 v90, v198, v88
	v_mul_f32_e32 v93, v7, v91
	v_mul_f32_e32 v91, v100, v88
	v_mul_f32_e32 v96, v102, v88
	v_mul_f32_e32 v97, v104, v88
	v_mul_f32_e32 v100, v106, v88
	v_mul_f32_e32 v101, v110, v88
	v_mul_f32_e32 v102, v114, v88
	v_mul_f32_e32 v103, v118, v88
	v_mul_f32_e32 v104, v122, v88
	v_mul_f32_e32 v105, v117, v88
	v_mul_f32_e32 v106, v116, v88
	v_mul_f32_e32 v95, v95, v88
	v_mul_f32_e32 v88, v94, v88
	v_mul_f32_e32 v89, v4, v89
	v_mul_f32_e32 v90, v5, v90
	v_mul_f32_e32 v94, v31, v88
	v_mov_b32_e32 v88, 0
	v_mul_f32_e32 v91, v12, v91
	v_mul_f32_e32 v96, v13, v96
	v_cvt_pk_fp8_f32 v88, v89, v90
	v_mov_b32_e32 v89, 0
	v_mul_f32_e32 v101, v20, v101
	v_mul_f32_e32 v102, v21, v102
	v_mul_f32_e32 v105, v28, v105
	v_mul_f32_e32 v106, v29, v106
	v_cvt_pk_fp8_f32 v89, v91, v96
	v_mov_b32_e32 v90, 0
	v_mov_b32_e32 v91, 0
	v_cvt_pk_fp8_f32 v90, v101, v102
	v_cvt_pk_fp8_f32 v91, v105, v106
	v_mul_f32_e32 v97, v14, v97
	v_mul_f32_e32 v100, v15, v100
	v_mul_f32_e32 v103, v22, v103
	v_mul_f32_e32 v104, v23, v104
	v_mul_f32_e32 v95, v30, v95
	v_cvt_pk_fp8_f32 v88, v92, v93 op_sel:[0,0,1]
	v_cvt_pk_fp8_f32 v89, v97, v100 op_sel:[0,0,1]
	v_cvt_pk_fp8_f32 v90, v103, v104 op_sel:[0,0,1]
	v_cvt_pk_fp8_f32 v91, v95, v94 op_sel:[0,0,1]
	s_andn2_b64 vcc, exec, s[20:21]
	global_store_dwordx4 v[98:99], v[88:91], off offset:1024 sc1
	s_cbranch_vccnz .LBB0_804
	s_nop 0
	v_lshlrev_b32_e32 v89, 16, v36
	v_lshlrev_b32_e32 v88, 16, v44
	v_lshlrev_b32_e32 v93, 16, v37
	v_mov_b32_e32 v98, v89
	v_lshlrev_b32_e32 v92, 16, v45
	v_lshlrev_b32_e32 v97, 16, v38
	v_pk_add_f32 v[102:103], v[98:99], v[88:89]
	v_mov_b32_e32 v88, v93
	v_lshlrev_b32_e32 v96, 16, v46
	v_lshlrev_b32_e32 v111, 16, v39
	v_pk_add_f32 v[100:101], v[88:89], v[92:93]
	v_mov_b32_e32 v88, v97
	v_lshlrev_b32_e32 v110, 16, v47
	v_and_b32_e32 v127, 0xffff0000, v39
	v_and_b32_e32 v126, 0xffff0000, v47
	v_pk_add_f32 v[96:97], v[88:89], v[96:97]
	v_mov_b32_e32 v88, v111
	v_lshlrev_b32_e32 v114, 16, v68
	v_pk_add_f32 v[92:93], v[88:89], v[110:111]
	v_pk_add_f32 v[88:89], v[126:127], v[126:127] op_sel:[1,0] op_sel_hi:[0,1]
	v_mul_f32_e32 v89, 0xbfb8aa3b, v114
	v_exp_f32_e32 v89, v89
	v_and_b32_e32 v95, 0xffff0000, v37
	v_and_b32_e32 v94, 0xffff0000, v45
	v_pk_add_f32 v[94:95], v[94:95], v[94:95] op_sel:[1,0] op_sel_hi:[0,1]
	v_add_f32_e32 v89, 1.0, v89
	v_div_scale_f32 v93, s[20:21], v89, v89, 1.0
	v_rcp_f32_e32 v95, v93
	v_and_b32_e32 v91, 0xffff0000, v36
	v_and_b32_e32 v90, 0xffff0000, v44
	v_and_b32_e32 v109, 0xffff0000, v38
	v_and_b32_e32 v108, 0xffff0000, v46
	v_pk_add_f32 v[98:99], v[90:91], v[90:91] op_sel:[1,0] op_sel_hi:[0,1]
	v_pk_add_f32 v[90:91], v[108:109], v[108:109] op_sel:[1,0] op_sel_hi:[0,1]
	v_and_b32_e32 v128, 0xffff0000, v68
	v_fma_f32 v91, -v93, v95, 1.0
	v_fmac_f32_e32 v95, v91, v95
	v_mul_f32_e32 v91, 0xbfb8aa3b, v128
	v_exp_f32_e32 v91, v91
	v_div_scale_f32 v97, vcc, 1.0, v89, 1.0
	v_pk_mul_f32 v[120:121], v[98:99], v[98:99]
	v_mul_f32_e32 v99, v97, v95
	v_fma_f32 v101, -v93, v99, v97
	v_add_f32_e32 v91, 1.0, v91
	v_fmac_f32_e32 v99, v101, v95
	v_div_scale_f32 v101, s[20:21], v91, v91, 1.0
	v_rcp_f32_e32 v103, v101
	v_fma_f32 v93, -v93, v99, v97
	v_lshlrev_b32_e32 v131, 16, v69
	v_div_fmas_f32 v93, v93, v95, v99
	v_fma_f32 v95, -v101, v103, 1.0
	v_fmac_f32_e32 v103, v95, v103
	v_mul_f32_e32 v95, 0xbfb8aa3b, v131
	v_exp_f32_e32 v95, v95
	v_lshlrev_b32_e32 v105, 16, v32
	v_lshlrev_b32_e32 v104, 16, v40
	v_and_b32_e32 v107, 0xffff0000, v32
	v_and_b32_e32 v106, 0xffff0000, v40
	v_mov_b32_e32 v108, v105
	v_div_scale_f32 v97, vcc, 1.0, v91, 1.0
	v_pk_add_f32 v[110:111], v[108:109], v[104:105]
	v_pk_add_f32 v[108:109], v[106:107], v[106:107] op_sel:[1,0] op_sel_hi:[0,1]
	v_mul_f32_e32 v99, v97, v103
	v_fma_f32 v109, -v101, v99, v97
	v_add_f32_e32 v95, 1.0, v95
	v_fmac_f32_e32 v99, v109, v103
	v_div_scale_f32 v109, s[20:21], v95, v95, 1.0
	v_rcp_f32_e32 v111, v109
	v_fma_f32 v97, -v101, v99, v97
	v_and_b32_e32 v132, 0xffff0000, v69
	v_div_fmas_f32 v97, v97, v103, v99
	v_fma_f32 v99, -v109, v111, 1.0
	v_fmac_f32_e32 v111, v99, v111
	v_mul_f32_e32 v99, 0xbfb8aa3b, v132
	v_exp_f32_e32 v99, v99
	v_div_scale_f32 v101, vcc, 1.0, v95, 1.0
	v_mul_f32_e32 v103, v101, v111
	v_fma_f32 v114, -v109, v103, v101
	v_add_f32_e32 v99, 1.0, v99
	v_fmac_f32_e32 v103, v114, v111
	v_div_scale_f32 v114, s[20:21], v99, v99, 1.0
	v_rcp_f32_e32 v121, v114
	v_fma_f32 v101, -v109, v103, v101
	v_lshlrev_b32_e32 v135, 16, v70
	v_div_fmas_f32 v101, v101, v111, v103
	v_fma_f32 v103, -v114, v121, 1.0
	v_fmac_f32_e32 v121, v103, v121
	v_mul_f32_e32 v103, 0xbfb8aa3b, v135
	v_exp_f32_e32 v103, v103
	v_div_scale_f32 v109, vcc, 1.0, v99, 1.0
	v_lshlrev_b32_e32 v123, 16, v34
	v_lshlrev_b32_e32 v125, 16, v42
	v_and_b32_e32 v122, 0xffff0000, v34
	v_and_b32_e32 v124, 0xffff0000, v42
	v_mul_f32_e32 v111, v109, v121
	v_pk_add_f32 v[104:105], v[124:125], v[122:123]
	v_fma_f32 v122, -v114, v111, v109
	v_add_f32_e32 v103, 1.0, v103
	v_fmac_f32_e32 v111, v122, v121
	v_div_scale_f32 v122, s[20:21], v103, v103, 1.0
	v_rcp_f32_e32 v123, v122
	v_fma_f32 v109, -v114, v111, v109
	v_and_b32_e32 v136, 0xffff0000, v70
	v_div_fmas_f32 v109, v109, v121, v111
	v_fma_f32 v111, -v122, v123, 1.0
	v_fmac_f32_e32 v123, v111, v123
	v_mul_f32_e32 v111, 0xbfb8aa3b, v136
	v_exp_f32_e32 v111, v111
	v_div_scale_f32 v114, vcc, 1.0, v103, 1.0
	v_mul_f32_e32 v121, v114, v123
	v_fma_f32 v124, -v122, v121, v114
	v_add_f32_e32 v111, 1.0, v111
	v_fmac_f32_e32 v121, v124, v123
	v_div_scale_f32 v124, s[20:21], v111, v111, 1.0
	v_rcp_f32_e32 v125, v124
	v_lshlrev_b32_e32 v139, 16, v71
	v_fma_f32 v114, -v122, v121, v114
	v_mul_f32_e32 v122, 0xbfb8aa3b, v139
	v_exp_f32_e32 v122, v122
	v_div_fmas_f32 v121, v114, v123, v121
	v_fma_f32 v114, -v124, v125, 1.0
	v_fmac_f32_e32 v125, v114, v125
	v_div_scale_f32 v114, vcc, 1.0, v111, 1.0
	v_mul_f32_e32 v123, v114, v125
	v_fma_f32 v126, -v124, v123, v114
	v_add_f32_e32 v164, 1.0, v122
	v_fmac_f32_e32 v123, v126, v125
	v_div_scale_f32 v122, s[20:21], v164, v164, 1.0
	v_and_b32_e32 v140, 0xffff0000, v71
	v_rcp_f32_e32 v126, v122
	v_fma_f32 v114, -v124, v123, v114
	v_div_fmas_f32 v165, v114, v125, v123
	v_mul_f32_e32 v123, 0xbfb8aa3b, v140
	v_exp_f32_e32 v123, v123
	v_fma_f32 v114, -v122, v126, 1.0
	v_fmac_f32_e32 v126, v114, v126
	v_div_scale_f32 v114, vcc, 1.0, v164, 1.0
	v_mul_f32_e32 v124, v114, v126
	v_add_f32_e32 v166, 1.0, v123
	v_fma_f32 v125, -v122, v124, v114
	v_div_scale_f32 v123, s[20:21], v166, v166, 1.0
	v_lshlrev_b32_e32 v129, 16, v64
	v_fmac_f32_e32 v124, v125, v126
	v_rcp_f32_e32 v125, v123
	v_fma_f32 v114, -v122, v124, v114
	v_mul_f32_e32 v122, 0xbfb8aa3b, v129
	v_exp_f32_e32 v122, v122
	v_div_fmas_f32 v167, v114, v126, v124
	v_fma_f32 v114, -v123, v125, 1.0
	v_fmac_f32_e32 v125, v114, v125
	v_div_scale_f32 v114, vcc, 1.0, v166, 1.0
	v_mul_f32_e32 v124, v114, v125
	v_add_f32_e32 v168, 1.0, v122
	v_fma_f32 v126, -v123, v124, v114
	v_div_scale_f32 v122, s[20:21], v168, v168, 1.0
	v_and_b32_e32 v130, 0xffff0000, v64
	v_fmac_f32_e32 v124, v126, v125
	v_rcp_f32_e32 v126, v122
	v_fma_f32 v114, -v123, v124, v114
	v_mul_f32_e32 v123, 0xbfb8aa3b, v130
	v_exp_f32_e32 v123, v123
	v_div_fmas_f32 v169, v114, v125, v124
	v_fma_f32 v114, -v122, v126, 1.0
	v_fmac_f32_e32 v126, v114, v126
	v_div_scale_f32 v114, vcc, 1.0, v168, 1.0
	v_mul_f32_e32 v124, v114, v126
	v_add_f32_e32 v176, 1.0, v123
	v_fma_f32 v125, -v122, v124, v114
	v_div_scale_f32 v123, s[20:21], v176, v176, 1.0
	v_lshlrev_b32_e32 v133, 16, v65
	v_fmac_f32_e32 v124, v125, v126
	v_rcp_f32_e32 v125, v123
	v_fma_f32 v114, -v122, v124, v114
	v_mul_f32_e32 v122, 0xbfb8aa3b, v133
	v_exp_f32_e32 v122, v122
	v_div_fmas_f32 v177, v114, v126, v124
	v_fma_f32 v114, -v123, v125, 1.0
	v_fmac_f32_e32 v125, v114, v125
	v_div_scale_f32 v114, vcc, 1.0, v176, 1.0
	v_mul_f32_e32 v124, v114, v125
	v_add_f32_e32 v178, 1.0, v122
	v_fma_f32 v126, -v123, v124, v114
	v_div_scale_f32 v122, s[20:21], v178, v178, 1.0
	v_and_b32_e32 v134, 0xffff0000, v65
	v_fmac_f32_e32 v124, v126, v125
	v_rcp_f32_e32 v126, v122
	v_fma_f32 v114, -v123, v124, v114
	v_mul_f32_e32 v123, 0xbfb8aa3b, v134
	v_exp_f32_e32 v123, v123
	v_div_fmas_f32 v179, v114, v125, v124
	v_fma_f32 v114, -v122, v126, 1.0
	v_fmac_f32_e32 v126, v114, v126
	v_div_scale_f32 v114, vcc, 1.0, v178, 1.0
	v_mul_f32_e32 v124, v114, v126
	v_add_f32_e32 v180, 1.0, v123
	v_fma_f32 v125, -v122, v124, v114
	v_div_scale_f32 v123, s[20:21], v180, v180, 1.0
	v_lshlrev_b32_e32 v137, 16, v66
	v_fmac_f32_e32 v124, v125, v126
	v_rcp_f32_e32 v125, v123
	v_fma_f32 v114, -v122, v124, v114
	v_mul_f32_e32 v122, 0xbfb8aa3b, v137
	v_exp_f32_e32 v122, v122
	v_div_fmas_f32 v181, v114, v126, v124
	v_fma_f32 v114, -v123, v125, 1.0
	v_fmac_f32_e32 v125, v114, v125
	v_div_scale_f32 v114, vcc, 1.0, v180, 1.0
	v_mul_f32_e32 v124, v114, v125
	v_add_f32_e32 v182, 1.0, v122
	v_fma_f32 v126, -v123, v124, v114
	v_div_scale_f32 v122, s[20:21], v182, v182, 1.0
	v_and_b32_e32 v138, 0xffff0000, v66
	v_fmac_f32_e32 v124, v126, v125
	v_rcp_f32_e32 v126, v122
	v_fma_f32 v114, -v123, v124, v114
	v_mul_f32_e32 v123, 0xbfb8aa3b, v138
	v_exp_f32_e32 v123, v123
	v_div_fmas_f32 v183, v114, v125, v124
	v_fma_f32 v114, -v122, v126, 1.0
	v_fmac_f32_e32 v126, v114, v126
	v_div_scale_f32 v114, vcc, 1.0, v182, 1.0
	v_mul_f32_e32 v124, v114, v126
	v_add_f32_e32 v186, 1.0, v123
	v_fma_f32 v125, -v122, v124, v114
	v_div_scale_f32 v123, s[20:21], v186, v186, 1.0
	v_lshlrev_b32_e32 v141, 16, v67
	v_fmac_f32_e32 v124, v125, v126
	v_rcp_f32_e32 v125, v123
	v_fma_f32 v114, -v122, v124, v114
	v_mul_f32_e32 v122, 0xbfb8aa3b, v141
	v_exp_f32_e32 v122, v122
	v_div_fmas_f32 v187, v114, v126, v124
	v_fma_f32 v114, -v123, v125, 1.0
	v_fmac_f32_e32 v125, v114, v125
	v_div_scale_f32 v114, vcc, 1.0, v186, 1.0
	v_mul_f32_e32 v124, v114, v125
	v_add_f32_e32 v188, 1.0, v122
	v_fma_f32 v126, -v123, v124, v114
	v_div_scale_f32 v122, s[20:21], v188, v188, 1.0
	v_and_b32_e32 v142, 0xffff0000, v67
	v_fmac_f32_e32 v124, v126, v125
	v_rcp_f32_e32 v126, v122
	v_fma_f32 v114, -v123, v124, v114
	v_mul_f32_e32 v123, 0xbfb8aa3b, v142
	v_exp_f32_e32 v123, v123
	v_div_fmas_f32 v189, v114, v125, v124
	v_fma_f32 v114, -v122, v126, 1.0
	v_fmac_f32_e32 v126, v114, v126
	v_div_scale_f32 v114, vcc, 1.0, v188, 1.0
	v_mul_f32_e32 v124, v114, v126
	v_add_f32_e32 v190, 1.0, v123
	v_fma_f32 v125, -v122, v124, v114
	v_div_scale_f32 v123, s[20:21], v190, v190, 1.0
	v_fmac_f32_e32 v124, v125, v126
	v_rcp_f32_e32 v125, v123
	v_fma_f32 v114, -v122, v124, v114
	v_div_fmas_f32 v191, v114, v126, v124
	v_lshlrev_b32_e32 v131, 16, v56
	v_fma_f32 v114, -v123, v125, 1.0
	v_fmac_f32_e32 v125, v114, v125
	v_div_scale_f32 v114, vcc, 1.0, v190, 1.0
	v_mul_f32_e32 v122, v114, v125
	v_fma_f32 v124, -v123, v122, v114
	v_fmac_f32_e32 v122, v124, v125
	v_fma_f32 v114, -v123, v122, v114
	v_lshlrev_b32_e32 v132, 16, v48
	v_and_b32_e32 v135, 0xffff0000, v53
	v_and_b32_e32 v136, 0xffff0000, v61
	v_lshlrev_b32_e32 v157, 16, v62
	v_lshlrev_b32_e32 v158, 16, v54
	v_and_b32_e32 v159, 0xffff0000, v54
	v_and_b32_e32 v160, 0xffff0000, v62
	v_div_fmas_f32 v192, v114, v125, v122
	v_and_b32_e32 v114, 0xffff0000, v52
	v_and_b32_e32 v130, 0xffff0000, v60
	v_add_f32_e32 v135, v135, v136
	v_add_f32_e32 v136, v158, v157
	v_add_f32_e32 v157, v159, v160
	v_add_f32_e32 v160, v132, v131
	v_and_b32_e32 v132, 0xffff0000, v76
	v_add_f32_e32 v114, v114, v130
	v_mul_f32_e32 v130, 0xbfb8aa3b, v132
	v_exp_f32_e32 v130, v130
	v_and_b32_e32 v133, 0xffff0000, v48
	v_and_b32_e32 v134, 0xffff0000, v56
	v_lshlrev_b32_e32 v161, 16, v63
	v_lshlrev_b32_e32 v162, 16, v55
	v_add_f32_e32 v158, v162, v161
	v_add_f32_e32 v161, v133, v134
	v_add_f32_e32 v133, 1.0, v130
	v_div_scale_f32 v130, s[20:21], v133, v133, v132
	v_rcp_f32_e32 v131, v130
	v_and_b32_e32 v143, 0xffff0000, v49
	v_and_b32_e32 v156, 0xffff0000, v57
	v_and_b32_e32 v163, 0xffff0000, v55
	v_fma_f32 v162, -v130, v131, 1.0
	v_and_b32_e32 v193, 0xffff0000, v63
	v_fmac_f32_e32 v131, v162, v131
	v_div_scale_f32 v162, vcc, v132, v133, v132
	v_and_b32_e32 v199, 0xffff0000, v81
	v_add_f32_e32 v159, v163, v193
	v_add_f32_e32 v143, v143, v156
	v_mul_f32_e32 v193, v162, v131
	v_fmac_f32_e32 v143, v144, v199
	v_fma_f32 v199, -v130, v193, v162
	v_lshlrev_b32_e32 v200, 16, v86
	v_fmac_f32_e32 v193, v199, v131
	v_fmac_f32_e32 v136, v144, v200
	v_fma_f32 v130, -v130, v193, v162
	v_lshlrev_b32_e32 v199, 16, v77
	v_lshlrev_b32_e32 v200, 16, v76
	v_div_fmas_f32 v162, v130, v131, v193
	v_mul_f32_e32 v130, 0xbfb8aa3b, v200
	v_mul_f32_e32 v131, 0xbfb8aa3b, v199
	v_exp_f32_e32 v130, v130
	v_exp_f32_e32 v131, v131
	v_and_b32_e32 v194, 0xffff0000, v84
	v_fmac_f32_e32 v114, v144, v194
	v_div_fixup_f32 v132, v162, v133, v132
	v_pk_add_f32 v[130:131], v[130:131], 1.0 op_sel_hi:[1,0]
	v_mul_f32_e32 v193, v132, v114
	v_div_scale_f32 v114, s[20:21], v131, v131, v199
	v_rcp_f32_e32 v162, v114
	v_lshlrev_b32_e32 v122, 16, v52
	v_lshlrev_b32_e32 v124, 16, v60
	v_lshlrev_b32_e32 v123, 16, v53
	v_lshlrev_b32_e32 v125, 16, v61
	v_pk_add_f32 v[122:123], v[124:125], v[122:123]
	v_fma_f32 v124, -v114, v162, 1.0
	v_fmac_f32_e32 v162, v124, v162
	v_div_scale_f32 v124, vcc, v199, v131, v199
	v_lshlrev_b32_e32 v133, 16, v85
	v_lshlrev_b32_e32 v132, 16, v84
	v_mul_f32_e32 v125, v124, v162
	v_pk_fma_f32 v[122:123], v[144:145], v[132:133], v[122:123]
	v_fma_f32 v132, -v114, v125, v124
	v_fmac_f32_e32 v125, v132, v162
	v_fma_f32 v114, -v114, v125, v124
	v_div_scale_f32 v124, s[20:21], v130, v130, v200
	v_rcp_f32_e32 v132, v124
	v_div_fmas_f32 v114, v114, v162, v125
	v_div_fixup_f32 v125, v114, v131, v199
	v_and_b32_e32 v134, 0xffff0000, v77
	v_fma_f32 v114, -v124, v132, 1.0
	v_fmac_f32_e32 v132, v114, v132
	v_div_scale_f32 v114, vcc, v200, v130, v200
	v_mul_f32_e32 v131, v114, v132
	v_fma_f32 v133, -v124, v131, v114
	v_fmac_f32_e32 v131, v133, v132
	v_fma_f32 v114, -v124, v131, v114
	v_mul_f32_e32 v124, 0xbfb8aa3b, v134
	v_exp_f32_e32 v133, v124
	v_div_fmas_f32 v114, v114, v132, v131
	v_div_fixup_f32 v124, v114, v130, v200
	v_pk_mul_f32 v[122:123], v[124:125], v[122:123]
	v_add_f32_e32 v114, 1.0, v133
	v_div_scale_f32 v130, s[20:21], v114, v114, v134
	v_rcp_f32_e32 v131, v130
	v_pk_mul_f32 v[124:125], v[122:123], v[122:123]
	v_lshlrev_b32_e32 v194, 16, v78
	v_fma_f32 v124, v193, v193, v124
	v_add_f32_e32 v162, v125, v124
	v_fma_f32 v124, -v130, v131, 1.0
	v_mul_f32_e32 v132, 0xbfb8aa3b, v194
	v_fmac_f32_e32 v131, v124, v131
	v_div_scale_f32 v124, vcc, v134, v114, v134
	v_exp_f32_e32 v132, v132
	v_mul_f32_e32 v125, v124, v131
	v_fma_f32 v133, -v130, v125, v124
	v_fmac_f32_e32 v125, v133, v131
	v_fma_f32 v124, -v130, v125, v124
	v_add_f32_e32 v130, 1.0, v132
	v_div_scale_f32 v132, s[20:21], v130, v130, v194
	v_rcp_f32_e32 v133, v132
	v_lshlrev_b32_e32 v195, 16, v80
	v_and_b32_e32 v197, 0xffff0000, v85
	v_fmac_f32_e32 v160, v144, v195
	v_and_b32_e32 v195, 0xffff0000, v78
	v_div_fmas_f32 v124, v124, v131, v125
	v_fmac_f32_e32 v135, v144, v197
	v_div_fixup_f32 v114, v124, v114, v134
	v_mul_f32_e32 v131, 0xbfb8aa3b, v195
	v_mul_f32_e32 v124, v114, v135
	v_fma_f32 v114, -v132, v133, 1.0
	v_exp_f32_e32 v131, v131
	v_fmac_f32_e32 v133, v114, v133
	v_div_scale_f32 v114, vcc, v194, v130, v194
	v_mul_f32_e32 v125, v114, v133
	v_fma_f32 v134, -v132, v125, v114
	v_fmac_f32_e32 v125, v134, v133
	v_add_f32_e32 v131, 1.0, v131
	v_fma_f32 v114, -v132, v125, v114
	v_div_scale_f32 v132, s[20:21], v131, v131, v195
	v_rcp_f32_e32 v134, v132
	v_lshlrev_b32_e32 v197, 16, v79
	v_div_fmas_f32 v114, v114, v133, v125
	v_mul_f32_e32 v133, 0xbfb8aa3b, v197
	v_div_fixup_f32 v114, v114, v130, v194
	v_exp_f32_e32 v133, v133
	v_mul_f32_e32 v130, v114, v136
	v_fma_f32 v114, -v132, v134, 1.0
	v_fmac_f32_e32 v134, v114, v134
	v_div_scale_f32 v114, vcc, v195, v131, v195
	v_mul_f32_e32 v125, v114, v134
	v_fma_f32 v135, -v132, v125, v114
	v_add_f32_e32 v133, 1.0, v133
	v_fmac_f32_e32 v125, v135, v134
	v_div_scale_f32 v135, s[20:21], v133, v133, v197
	v_lshlrev_b32_e32 v137, 16, v57
	v_lshlrev_b32_e32 v142, 16, v49
	v_rcp_f32_e32 v136, v135
	v_lshlrev_b32_e32 v198, 16, v81
	v_add_f32_e32 v137, v142, v137
	v_fma_f32 v114, -v132, v125, v114
	v_and_b32_e32 v201, 0xffff0000, v86
	v_fmac_f32_e32 v137, v144, v198
	v_and_b32_e32 v198, 0xffff0000, v79
	v_div_fmas_f32 v114, v114, v134, v125
	v_fmac_f32_e32 v157, v144, v201
	v_div_fixup_f32 v114, v114, v131, v195
	v_mul_f32_e32 v131, 0xbfb8aa3b, v198
	v_mul_f32_e32 v132, v114, v157
	v_fma_f32 v114, -v135, v136, 1.0
	v_exp_f32_e32 v131, v131
	v_fmac_f32_e32 v136, v114, v136
	v_div_scale_f32 v114, vcc, v197, v133, v197
	v_mul_f32_e32 v125, v114, v136
	v_fma_f32 v134, -v135, v125, v114
	v_fmac_f32_e32 v125, v134, v136
	v_add_f32_e32 v131, 1.0, v131
	v_fma_f32 v114, -v135, v125, v114
	v_div_scale_f32 v135, s[20:21], v131, v131, v198
	v_rcp_f32_e32 v157, v135
	v_lshlrev_b32_e32 v202, 16, v87
	v_lshlrev_b32_e32 v142, 16, v72
	v_div_fmas_f32 v114, v114, v136, v125
	v_fmac_f32_e32 v158, v144, v202
	v_div_fixup_f32 v114, v114, v133, v197
	v_mul_f32_e32 v133, 0xbfb8aa3b, v142
	v_mul_f32_e32 v134, v114, v158
	v_fma_f32 v114, -v135, v157, 1.0
	v_exp_f32_e32 v133, v133
	v_fmac_f32_e32 v157, v114, v157
	v_div_scale_f32 v114, vcc, v198, v131, v198
	v_mul_f32_e32 v125, v114, v157
	v_fma_f32 v136, -v135, v125, v114
	v_fmac_f32_e32 v125, v136, v157
	v_add_f32_e32 v133, 1.0, v133
	v_fma_f32 v114, -v135, v125, v114
	v_div_scale_f32 v135, s[20:21], v133, v133, v142
	v_rcp_f32_e32 v158, v135
	v_and_b32_e32 v203, 0xffff0000, v87
	v_and_b32_e32 v156, 0xffff0000, v72
	v_div_fmas_f32 v114, v114, v157, v125
	v_fmac_f32_e32 v159, v144, v203
	v_div_fixup_f32 v114, v114, v131, v198
	v_mul_f32_e32 v131, 0xbfb8aa3b, v156
	v_mul_f32_e32 v136, v114, v159
	v_fma_f32 v114, -v135, v158, 1.0
	v_exp_f32_e32 v131, v131
	v_fmac_f32_e32 v158, v114, v158
	v_div_scale_f32 v114, vcc, v142, v133, v142
	v_mul_f32_e32 v125, v114, v158
	v_fma_f32 v157, -v135, v125, v114
	v_fmac_f32_e32 v125, v157, v158
	v_add_f32_e32 v131, 1.0, v131
	v_fma_f32 v114, -v135, v125, v114
	v_div_scale_f32 v135, s[20:21], v131, v131, v156
	v_rcp_f32_e32 v157, v135
	v_lshlrev_b32_e32 v163, 16, v73
	v_div_fmas_f32 v114, v114, v158, v125
	v_div_fixup_f32 v114, v114, v133, v142
	v_mul_f32_e32 v133, 0xbfb8aa3b, v163
	v_mul_f32_e32 v142, v114, v160
	v_fma_f32 v114, -v135, v157, 1.0
	v_exp_f32_e32 v133, v133
	v_fmac_f32_e32 v157, v114, v157
	v_div_scale_f32 v114, vcc, v156, v131, v156
	v_mul_f32_e32 v125, v114, v157
	v_fma_f32 v158, -v135, v125, v114
	v_fmac_f32_e32 v125, v158, v157
	v_add_f32_e32 v133, 1.0, v133
	v_fma_f32 v114, -v135, v125, v114
	v_div_scale_f32 v135, s[20:21], v133, v133, v163
	v_rcp_f32_e32 v158, v135
	v_and_b32_e32 v196, 0xffff0000, v80
	v_fmac_f32_e32 v161, v144, v196
	v_and_b32_e32 v196, 0xffff0000, v73
	v_div_fmas_f32 v114, v114, v157, v125
	v_div_fixup_f32 v114, v114, v131, v156
	v_mul_f32_e32 v131, 0xbfb8aa3b, v196
	v_mul_f32_e32 v156, v114, v161
	v_fma_f32 v114, -v135, v158, 1.0
	v_exp_f32_e32 v131, v131
	v_fmac_f32_e32 v158, v114, v158
	v_div_scale_f32 v114, vcc, v163, v133, v163
	v_mul_f32_e32 v125, v114, v158
	v_fma_f32 v157, -v135, v125, v114
	v_fmac_f32_e32 v125, v157, v158
	v_add_f32_e32 v131, 1.0, v131
	v_fma_f32 v114, -v135, v125, v114
	v_div_scale_f32 v135, s[20:21], v131, v131, v196
	v_rcp_f32_e32 v157, v135
	v_div_fmas_f32 v114, v114, v158, v125
	v_div_fixup_f32 v114, v114, v133, v163
	v_mul_f32_e32 v158, v114, v137
	v_fma_f32 v114, -v135, v157, 1.0
	v_fmac_f32_e32 v157, v114, v157
	v_div_scale_f32 v114, vcc, v196, v131, v196
	v_mul_f32_e32 v125, v114, v157
	v_fma_f32 v133, -v135, v125, v114
	v_fmac_f32_e32 v125, v133, v157
	v_fma_f32 v114, -v135, v125, v114
	v_lshlrev_b32_e32 v133, 16, v74
	v_div_fmas_f32 v114, v114, v157, v125
	v_and_b32_e32 v125, 0xffff0000, v74
	v_mul_f32_e32 v135, 0xbfb8aa3b, v133
	v_exp_f32_e32 v195, v135
	v_mul_f32_e32 v135, 0xbfb8aa3b, v125
	v_exp_f32_e32 v194, v135
	v_div_fixup_f32 v114, v114, v131, v196
	v_mul_f32_e32 v160, v114, v143
	v_lshlrev_b32_e32 v139, 16, v50
	v_pk_add_f32 v[194:195], v[194:195], 1.0 op_sel_hi:[1,0]
	v_lshlrev_b32_e32 v141, 16, v58
	v_div_scale_f32 v114, s[20:21], v195, v195, v133
	v_rcp_f32_e32 v131, v114
	v_and_b32_e32 v138, 0xffff0000, v50
	v_and_b32_e32 v140, 0xffff0000, v58
	v_pk_add_f32 v[138:139], v[140:141], v[138:139]
	v_fma_f32 v135, -v114, v131, 1.0
	v_fmac_f32_e32 v131, v135, v131
	v_div_scale_f32 v135, vcc, v133, v195, v133
	v_mul_f32_e32 v137, v135, v131
	v_fma_f32 v140, -v114, v137, v135
	v_fmac_f32_e32 v137, v140, v131
	v_fma_f32 v114, -v114, v137, v135
	v_div_scale_f32 v135, s[20:21], v194, v194, v125
	v_rcp_f32_e32 v140, v135
	v_div_fmas_f32 v114, v114, v131, v137
	v_div_fixup_f32 v141, v114, v195, v133
	v_mov_b32_e32 v163, v120
	v_fma_f32 v114, -v135, v140, 1.0
	v_fmac_f32_e32 v140, v114, v140
	v_div_scale_f32 v114, vcc, v125, v194, v125
	v_mul_f32_e32 v131, v114, v140
	v_fma_f32 v133, -v135, v131, v114
	v_fmac_f32_e32 v131, v133, v140
	v_fma_f32 v114, -v135, v131, v114
	v_div_fmas_f32 v114, v114, v140, v131
	v_div_fixup_f32 v140, v114, v194, v125
	v_mov_b32_e32 v125, v102
	v_lshlrev_b32_e32 v120, 16, v75
	v_and_b32_e32 v196, 0xffff0000, v82
	v_lshlrev_b32_e32 v197, 16, v82
	v_pk_fma_f32 v[162:163], v[124:125], v[124:125], v[162:163]
	v_and_b32_e32 v114, 0xffff0000, v75
	v_mul_f32_e32 v125, 0xbfb8aa3b, v120
	v_pk_fma_f32 v[138:139], v[144:145], v[196:197], v[138:139]
	v_exp_f32_e32 v197, v125
	v_mul_f32_e32 v125, 0xbfb8aa3b, v114
	v_exp_f32_e32 v196, v125
	v_lshlrev_b32_e32 v117, 16, v33
	v_lshlrev_b32_e32 v119, 16, v41
	v_and_b32_e32 v116, 0xffff0000, v33
	v_and_b32_e32 v118, 0xffff0000, v41
	v_pk_add_f32 v[106:107], v[118:119], v[116:117]
	v_pk_add_f32 v[196:197], v[196:197], 1.0 op_sel_hi:[1,0]
	v_pk_mul_f32 v[118:119], v[106:107], v[106:107]
	v_lshlrev_b32_e32 v127, 16, v51
	v_mov_b32_e32 v195, v119
	v_div_scale_f32 v119, s[20:21], v197, v197, v120
	v_rcp_f32_e32 v125, v119
	v_lshlrev_b32_e32 v129, 16, v59
	v_and_b32_e32 v126, 0xffff0000, v51
	v_and_b32_e32 v128, 0xffff0000, v59
	v_pk_add_f32 v[126:127], v[128:129], v[126:127]
	v_fma_f32 v128, -v119, v125, 1.0
	v_fmac_f32_e32 v125, v128, v125
	v_div_scale_f32 v128, vcc, v120, v197, v120
	v_mov_b32_e32 v131, v100
	v_mul_f32_e32 v129, v128, v125
	v_pk_fma_f32 v[162:163], v[130:131], v[130:131], v[162:163]
	v_fma_f32 v131, -v119, v129, v128
	v_fmac_f32_e32 v129, v131, v125
	v_fma_f32 v119, -v119, v129, v128
	v_div_scale_f32 v128, s[20:21], v196, v196, v114
	v_rcp_f32_e32 v131, v128
	v_mov_b32_e32 v133, v94
	v_pk_fma_f32 v[162:163], v[132:133], v[132:133], v[162:163]
	v_mov_b32_e32 v135, v96
	v_div_fmas_f32 v119, v119, v125, v129
	v_pk_fma_f32 v[162:163], v[134:135], v[134:135], v[162:163]
	v_mov_b32_e32 v137, v90
	v_div_fixup_f32 v129, v119, v197, v120
	v_fma_f32 v119, -v128, v131, 1.0
	v_pk_fma_f32 v[162:163], v[136:137], v[136:137], v[162:163]
	v_mov_b32_e32 v143, v92
	v_fmac_f32_e32 v131, v119, v131
	v_div_scale_f32 v119, vcc, v114, v196, v114
	v_pk_fma_f32 v[162:163], v[142:143], v[142:143], v[162:163]
	v_mov_b32_e32 v157, v88
	v_mul_f32_e32 v120, v119, v131
	v_pk_mul_f32 v[138:139], v[140:141], v[138:139]
	v_pk_fma_f32 v[162:163], v[156:157], v[156:157], v[162:163]
	v_mov_b32_e32 v159, v110
	v_fma_f32 v125, -v128, v120, v119
	v_pk_mul_f32 v[140:141], v[138:139], v[138:139]
	v_pk_fma_f32 v[162:163], v[158:159], v[158:159], v[162:163]
	v_mov_b32_e32 v161, v108
	v_fmac_f32_e32 v120, v125, v131
	v_pk_fma_f32 v[162:163], v[160:161], v[160:161], v[162:163]
	v_mov_b32_e32 v194, v141
	v_fma_f32 v119, -v128, v120, v119
	v_pk_add_f32 v[162:163], v[194:195], v[162:163]
	v_and_b32_e32 v194, 0xffff0000, v83
	v_lshlrev_b32_e32 v195, 16, v83
	v_div_fmas_f32 v119, v119, v131, v120
	v_pk_fma_f32 v[126:127], v[144:145], v[194:195], v[126:127]
	v_div_fixup_f32 v128, v119, v196, v114
	v_pk_mul_f32 v[126:127], v[128:129], v[126:127]
	v_pk_mul_f32 v[116:117], v[104:105], v[104:105]
	v_pk_mul_f32 v[128:129], v[126:127], v[126:127]
	v_mov_b32_e32 v141, v118
	v_pk_add_f32 v[118:119], v[140:141], v[162:163]
	v_mov_b32_e32 v140, v129
	v_mov_b32_e32 v141, v117
	v_pk_add_f32 v[118:119], v[140:141], v[118:119]
	v_mov_b32_e32 v129, v116
	v_pk_add_f32 v[116:117], v[128:129], v[118:119]
	ds_bpermute_b32 v118, v170, v116
	v_lshlrev_b32_e32 v113, 16, v35
	v_lshlrev_b32_e32 v115, 16, v43
	v_and_b32_e32 v112, 0xffff0000, v35
	v_and_b32_e32 v114, 0xffff0000, v43
	v_pk_add_f32 v[112:113], v[114:115], v[112:113]
	v_div_fixup_f32 v89, v93, v89, 1.0
	v_pk_mul_f32 v[114:115], v[112:113], v[112:113]
	v_div_fixup_f32 v91, v97, v91, 1.0
	v_mov_b32_e32 v119, v115
	s_waitcnt lgkmcnt(0)
	v_pk_add_f32 v[116:117], v[116:117], v[118:119]
	ds_bpermute_b32 v118, v171, v116
	v_mov_b32_e32 v119, v114
	v_div_fixup_f32 v93, v101, v95, 1.0
	v_div_fixup_f32 v95, v109, v99, 1.0
	v_div_fixup_f32 v97, v121, v103, 1.0
	s_waitcnt lgkmcnt(0)
	v_pk_add_f32 v[114:115], v[116:117], v[118:119]
	ds_bpermute_b32 v117, v170, v115
	ds_bpermute_b32 v116, v172, v114
	v_div_fixup_f32 v103, v169, v166, 1.0
	v_div_fixup_f32 v109, v177, v168, 1.0
	v_div_fixup_f32 v99, v165, v111, 1.0
	v_div_fixup_f32 v111, v179, v176, 1.0
	s_waitcnt lgkmcnt(0)
	v_pk_add_f32 v[114:115], v[114:115], v[116:117]
	ds_bpermute_b32 v117, v171, v115
	ds_bpermute_b32 v116, v173, v114
	v_div_fixup_f32 v118, v181, v178, 1.0
	v_div_fixup_f32 v119, v183, v180, 1.0
	v_div_fixup_f32 v101, v167, v164, 1.0
	v_div_fixup_f32 v120, v187, v182, 1.0
	s_waitcnt lgkmcnt(0)
	v_pk_add_f32 v[114:115], v[114:115], v[116:117]
	ds_bpermute_b32 v117, v172, v115
	ds_bpermute_b32 v116, v174, v114
	v_div_fixup_f32 v121, v189, v186, 1.0
	s_ashr_i32 s15, s14, 31
	s_lshl_b64 s[20:21], s[14:15], 11
	s_waitcnt lgkmcnt(0)
	v_pk_add_f32 v[114:115], v[114:115], v[116:117]
	ds_bpermute_b32 v117, v173, v115
	ds_bpermute_b32 v116, v175, v114
	s_waitcnt lgkmcnt(0)
	v_pk_add_f32 v[114:115], v[114:115], v[116:117]
	s_nop 0
	v_pk_fma_f32 v[114:115], v[114:115], s[12:13], v[154:155] op_sel_hi:[1,1,0]
	v_div_fixup_f32 v117, v192, v190, 1.0
	v_mul_f32_e32 v116, 0x4b800000, v115
	v_cmp_gt_f32_e32 vcc, s19, v115
	s_nop 1
	v_cndmask_b32_e32 v115, v115, v116, vcc
	v_rsq_f32_e32 v115, v115
	v_div_fixup_f32 v116, v191, v188, 1.0
	v_mul_f32_e32 v125, 0x45800000, v115
	v_cndmask_b32_e32 v115, v115, v125, vcc
	v_mul_f32_e32 v94, v94, v115
	v_mul_f32_e32 v88, v88, v115
	v_mul_f32_e32 v94, v3, v94
	v_mul_f32_e32 v88, v11, v88
	v_mul_f32_e32 v98, v98, v115
	v_mul_f32_e32 v94, v95, v94
	v_mul_f32_e32 v95, v96, v115
	v_mul_f32_e32 v96, v103, v88
	v_mul_f32_e32 v88, v110, v115
	v_mul_f32_e32 v98, v1, v98
	v_mul_f32_e32 v95, v8, v95
	v_mul_f32_e32 v88, v16, v88
	v_mul_f32_e32 v91, v91, v98
	v_mul_f32_e32 v98, v100, v115
	v_mul_f32_e32 v95, v97, v95
	v_mul_f32_e32 v97, v109, v88
	v_mul_f32_e32 v88, v108, v115
	v_mul_f32_e32 v98, v2, v98
	v_mul_f32_e32 v88, v17, v88
	v_mul_f32_e32 v93, v93, v98
	v_mul_f32_e32 v90, v90, v115
	v_mul_f32_e32 v98, v111, v88
	v_mul_f32_e32 v88, v107, v115
	v_mul_f32_e32 v90, v9, v90
	v_mul_f32_e32 v88, v18, v88
	v_mul_f32_e32 v90, v99, v90
	v_mul_f32_e32 v99, v118, v88
	v_mul_f32_e32 v88, v106, v115
	v_mul_f32_e32 v88, v19, v88
	v_mul_f32_e32 v92, v92, v115
	v_mul_f32_e32 v100, v119, v88
	v_mul_f32_e32 v88, v105, v115
	v_mul_f32_e32 v92, v10, v92
	v_mul_f32_e32 v88, v24, v88
	v_mul_f32_e32 v102, v102, v115
	v_mul_f32_e32 v92, v101, v92
	v_mul_f32_e32 v101, v120, v88
	v_mul_f32_e32 v88, v104, v115
	v_mul_f32_e32 v102, v0, v102
	v_mul_f32_e32 v88, v25, v88
	v_mul_f32_e32 v89, v89, v102
	v_mul_f32_e32 v102, v121, v88
	v_mul_f32_e32 v88, v113, v115
	v_mul_f32_e32 v88, v26, v88
	v_mul_f32_e32 v103, v116, v88
	v_mov_b32_e32 v88, 0
	v_cvt_pk_fp8_f32 v88, v89, v91
	v_mul_f32_e32 v89, v112, v115
	v_mul_f32_e32 v89, v27, v89
	v_cmp_gt_f32_e32 vcc, s19, v114
	v_cvt_pk_fp8_f32 v88, v93, v94 op_sel:[0,0,1]
	v_mul_f32_e32 v93, 0x4b800000, v114
	v_mul_f32_e32 v104, v117, v89
	v_mov_b32_e32 v89, 0
	v_cndmask_b32_e32 v93, v114, v93, vcc
	v_cvt_pk_fp8_f32 v89, v95, v90
	v_rsq_f32_e32 v93, v93
	v_mov_b32_e32 v90, 0
	v_mov_b32_e32 v91, 0
	v_cvt_pk_fp8_f32 v90, v97, v98
	v_cvt_pk_fp8_f32 v91, v101, v102
	v_cvt_pk_fp8_f32 v89, v92, v96 op_sel:[0,0,1]
	v_mul_f32_e32 v92, 0x45800000, v93
	v_cndmask_b32_e32 v92, v93, v92, vcc
	v_mul_f32_e32 v95, v123, v92
	v_mul_f32_e32 v96, v6, v95
	v_mul_f32_e32 v95, v124, v92
	v_cvt_pk_fp8_f32 v90, v99, v100 op_sel:[0,0,1]
	v_cvt_pk_fp8_f32 v91, v103, v104 op_sel:[0,0,1]
	v_mul_f32_e32 v93, v122, v92
	v_mul_f32_e32 v94, v193, v92
	v_mul_f32_e32 v97, v7, v95
	v_mul_f32_e32 v95, v130, v92
	v_mul_f32_e32 v98, v132, v92
	v_mul_f32_e32 v99, v134, v92
	v_mul_f32_e32 v100, v136, v92
	v_mul_f32_e32 v101, v142, v92
	v_mul_f32_e32 v102, v156, v92
	v_mul_f32_e32 v103, v158, v92
	v_mul_f32_e32 v104, v160, v92
	v_mul_f32_e32 v105, v139, v92
	v_mul_f32_e32 v106, v138, v92
	v_mul_f32_e32 v107, v127, v92
	v_mul_f32_e32 v92, v126, v92
	v_mul_f32_e32 v93, v4, v93
	v_mul_f32_e32 v94, v5, v94
	v_mul_f32_e32 v108, v31, v92
	v_mov_b32_e32 v92, 0
	v_mul_f32_e32 v95, v12, v95
	v_mul_f32_e32 v98, v13, v98
	v_cvt_pk_fp8_f32 v92, v93, v94
	v_mov_b32_e32 v93, 0
	v_mul_f32_e32 v101, v20, v101
	v_mul_f32_e32 v102, v21, v102
	v_mul_f32_e32 v105, v28, v105
	v_mul_f32_e32 v106, v29, v106
	v_cvt_pk_fp8_f32 v93, v95, v98
	v_mov_b32_e32 v94, 0
	v_mov_b32_e32 v95, 0
	v_cvt_pk_fp8_f32 v94, v101, v102
	v_cvt_pk_fp8_f32 v95, v105, v106
	v_mul_f32_e32 v99, v14, v99
	v_mul_f32_e32 v100, v15, v100
	v_mul_f32_e32 v103, v22, v103
	v_mul_f32_e32 v104, v23, v104
	v_mul_f32_e32 v107, v30, v107
	v_cvt_pk_fp8_f32 v92, v96, v97 op_sel:[0,0,1]
	v_cvt_pk_fp8_f32 v93, v99, v100 op_sel:[0,0,1]
	v_cvt_pk_fp8_f32 v94, v103, v104 op_sel:[0,0,1]
	v_cvt_pk_fp8_f32 v95, v107, v108 op_sel:[0,0,1]
	v_lshl_add_u64 v[96:97], v[148:149], 0, s[20:21]
	global_store_dwordx4 v[96:97], v[88:91], off sc1
	global_store_dwordx4 v[96:97], v[92:95], off offset:1024 sc1
	s_branch .LBB0_804

.LBB0_997:
	s_add_i32 s0, s4, 0xfffff000
	s_lshr_b32 s17, s0, 11
	s_add_i32 s17, s17, 1
	s_cmpk_lt_i32 s4, 0x1000
	s_cselect_b32 s19, s5, 0
	s_cselect_b32 s18, s4, s0
	s_cselect_b32 s0, s37, s39
	s_cselect_b32 s20, s36, s38
	s_cselect_b32 s17, 0, s17
	s_lshl_b64 s[18:19], s[18:19], 13
	s_add_u32 s18, s20, s18
	s_addc_u32 s19, s0, s19
	s_mul_i32 s0, s17, 0x1800
	s_lshl_b64 s[20:21], s[0:1], 2
	s_add_u32 s20, s3, s20
	s_mul_i32 s0, s17, 0x3000
	s_addc_u32 s21, s12, s21
	s_lshl_b64 s[22:23], s[0:1], 2
	s_add_u32 s0, s28, s22
	v_lshl_add_u64 v[160:161], s[28:29], 0, v[130:131]
	s_addc_u32 s17, s29, s23
	s_add_u32 s22, s0, 0x106000
	v_add_co_u32_e32 v52, vcc, s14, v160
	v_lshl_add_u64 v[32:33], s[18:19], 0, v[128:129]
	s_addc_u32 s23, s17, 0
	v_addc_co_u32_e32 v53, vcc, 0, v161, vcc
	s_add_u32 s24, s20, 0x2000
	v_add_co_u32_e32 v54, vcc, s13, v32
	s_addc_u32 s25, s21, 0
	s_nop 0
	v_addc_co_u32_e32 v55, vcc, 0, v33, vcc
	global_load_dwordx4 v[0:3], v180, s[24:25]
	global_load_dwordx4 v[4:7], v180, s[22:23]
	global_load_dwordx4 v[64:67], v128, s[18:19]
	global_load_dwordx4 v[68:71], v128, s[18:19] offset:1024
	global_load_dwordx4 v[76:79], v180, s[20:21]
	global_load_dwordx4 v[72:75], v180, s[20:21] offset:1024
	global_load_dwordx4 v[8:11], v181, s[24:25]
	global_load_dwordx4 v[12:15], v181, s[22:23]
	global_load_dwordx4 v[16:19], v182, s[24:25]
	global_load_dwordx4 v[20:23], v182, s[22:23]
	global_load_dwordx2 v[136:137], v[52:53], off
	global_load_dwordx2 v[138:139], v[52:53], off offset:512
	global_load_dwordx2 v[142:143], v[52:53], off offset:1024
	global_load_dwordx2 v[144:145], v[52:53], off offset:1536
	global_load_dwordx4 v[84:87], v128, s[18:19] offset:2048
	global_load_dwordx4 v[80:83], v128, s[18:19] offset:3072
	global_load_dwordx4 v[92:95], v180, s[20:21] offset:2048
	global_load_dwordx4 v[88:91], v180, s[20:21] offset:3072
	global_load_dwordx4 v[24:27], v183, s[24:25]
	global_load_dwordx4 v[28:31], v183, s[22:23]
	global_load_dwordx4 v[96:99], v186, s[20:21]
	global_load_dwordx4 v[32:35], v186, s[22:23]
	global_load_dwordx4 v[100:103], v[54:55], off
	global_load_dwordx4 v[104:107], v[54:55], off offset:1024
	global_load_dwordx4 v[36:39], v186, s[24:25]
	global_load_dwordx4 v[108:111], v187, s[20:21]
	global_load_dwordx4 v[40:43], v187, s[24:25]
	global_load_dwordx4 v[44:47], v187, s[22:23]
	global_load_dwordx4 v[112:115], v188, s[20:21]
	global_load_dwordx4 v[48:51], v188, s[22:23]
	global_load_dwordx2 v[148:149], v[52:53], off offset:2048
	global_load_dwordx2 v[154:155], v[52:53], off offset:2560
	global_load_dwordx2 v[158:159], v[52:53], off offset:3072
	global_load_dwordx2 v[162:163], v[52:53], off offset:3584
	global_load_dwordx4 v[120:123], v[54:55], off offset:2048
	global_load_dwordx4 v[116:119], v[54:55], off offset:3072
	s_nop 0
	global_load_dwordx4 v[52:55], v188, s[24:25]
	global_load_dwordx4 v[124:127], v189, s[20:21]
	global_load_dwordx4 v[56:59], v189, s[24:25]
	global_load_dwordx4 v[60:63], v189, s[22:23]
	s_waitcnt vmcnt(29)
	v_lshlrev_b32_e32 v134, 16, v136
	v_and_b32_e32 v135, 0xffff0000, v136
	v_lshlrev_b32_e32 v136, 16, v137
	v_and_b32_e32 v137, 0xffff0000, v137
	s_waitcnt vmcnt(28)
	v_lshlrev_b32_e32 v153, 16, v139
	v_lshlrev_b32_e32 v152, 16, v138
	v_and_b32_e32 v139, 0xffff0000, v139
	v_and_b32_e32 v138, 0xffff0000, v138
	s_waitcnt vmcnt(27)
	v_and_b32_e32 v141, 0xffff0000, v142
	s_waitcnt vmcnt(26)
	v_lshlrev_b32_e32 v151, 16, v144
	s_waitcnt vmcnt(6)
	v_lshlrev_b32_e32 v169, 16, v162
	v_mul_f32_e32 v150, v137, v137
	v_pk_mul_f32 v[192:193], v[138:139], v[138:139]
	v_mul_f32_e32 v168, v135, v135
	v_lshlrev_b32_e32 v140, 16, v142
	v_lshlrev_b32_e32 v142, 16, v143
	v_and_b32_e32 v143, 0xffff0000, v143
	v_mov_b32_e32 v195, v151
	v_mul_f32_e32 v194, v141, v141
	v_mov_b32_e32 v206, v152
	v_mov_b32_e32 v207, v138
	v_mov_b32_e32 v138, v153
	v_pk_fma_f32 v[212:213], v[136:137], v[136:137], v[150:151] op_sel_hi:[1,1,0]
	v_pk_fma_f32 v[152:153], v[152:153], v[152:153], v[192:193]
	v_pk_fma_f32 v[192:193], v[134:135], v[134:135], v[168:169] op_sel_hi:[1,1,0]
	v_and_b32_e32 v147, 0xffff0000, v144
	v_lshlrev_b32_e32 v144, 16, v145
	v_and_b32_e32 v145, 0xffff0000, v145
	v_mul_f32_e32 v196, v143, v143
	v_mov_b32_e32 v197, v169
	v_pk_fma_f32 v[214:215], v[140:141], v[140:141], v[194:195] op_sel_hi:[1,1,0]
	v_mov_b32_e32 v150, v192
	v_mov_b32_e32 v194, v212
	v_mul_f32_e32 v223, v147, v147
	v_mul_f32_e32 v224, v144, v144
	v_mul_f32_e32 v225, v145, v145
	v_mov_b32_e32 v146, v151
	v_pk_fma_f32 v[216:217], v[142:143], v[142:143], v[196:197] op_sel_hi:[1,1,0]
	v_pk_add_f32 v[192:193], v[192:193], v[212:213]
	v_pk_add_f32 v[152:153], v[152:153], v[152:153] op_sel:[0,1] op_sel_hi:[1,0]
	v_pk_mul_f32 v[150:151], v[150:151], v[194:195]
	v_lshlrev_b32_e32 v167, 16, v149
	v_lshlrev_b32_e32 v166, 16, v148
	v_and_b32_e32 v149, 0xffff0000, v149
	v_and_b32_e32 v148, 0xffff0000, v148
	v_mov_b32_e32 v215, v224
	v_mov_b32_e32 v217, v225
	v_mov_b32_e32 v153, v223
	v_mov_b32_e32 v193, v151
	v_pk_mul_f32 v[198:199], v[148:149], v[148:149]
	v_pk_add_f32 v[194:195], v[214:215], v[216:217]
	v_pk_add_f32 v[150:151], v[192:193], v[152:153]
	v_lshlrev_b32_e32 v171, 16, v155
	v_lshlrev_b32_e32 v170, 16, v154
	v_and_b32_e32 v155, 0xffff0000, v155
	v_and_b32_e32 v154, 0xffff0000, v154
	v_mov_b32_e32 v208, v166
	v_mov_b32_e32 v209, v148
	v_mov_b32_e32 v148, v167
	v_pk_fma_f32 v[166:167], v[166:167], v[166:167], v[198:199]
	v_pk_add_f32 v[150:151], v[150:151], v[194:195]
	v_lshlrev_b32_e32 v156, 16, v158
	v_and_b32_e32 v157, 0xffff0000, v158
	v_lshlrev_b32_e32 v158, 16, v159
	v_and_b32_e32 v159, 0xffff0000, v159
	v_pk_mul_f32 v[200:201], v[154:155], v[154:155]
	v_pk_add_f32 v[166:167], v[166:167], v[166:167] op_sel:[0,1] op_sel_hi:[1,0]
	v_pk_add_f32 v[150:151], v[150:151], v[150:151] op_sel:[0,1] op_sel_hi:[1,0]
	v_and_b32_e32 v165, 0xffff0000, v162
	v_lshlrev_b32_e32 v162, 16, v163
	v_and_b32_e32 v163, 0xffff0000, v163
	v_mov_b32_e32 v203, 0
	v_mov_b32_e32 v205, 0
	v_mul_f32_e32 v202, v157, v157
	v_mul_f32_e32 v204, v159, v159
	v_mov_b32_e32 v210, v170
	v_mov_b32_e32 v211, v154
	v_mov_b32_e32 v154, v171
	v_pk_fma_f32 v[170:171], v[170:171], v[170:171], v[200:201]
	v_mov_b32_e32 v196, v166
	v_mov_b32_e32 v168, v150
	v_mul_f32_e32 v226, v165, v165
	v_mul_f32_e32 v227, v162, v162
	v_mul_f32_e32 v228, v163, v163
	v_pk_fma_f32 v[198:199], v[156:157], v[156:157], v[202:203] op_sel_hi:[1,1,0]
	v_pk_fma_f32 v[200:201], v[158:159], v[158:159], v[204:205] op_sel_hi:[1,1,0]
	v_pk_add_f32 v[170:171], v[170:171], v[170:171] op_sel:[0,1] op_sel_hi:[1,0]
	v_pk_add_f32 v[150:151], v[150:151], v[166:167]
	v_pk_mul_f32 v[152:153], v[168:169], v[196:197]
	v_mov_b32_e32 v199, v227
	v_mov_b32_e32 v201, v228
	v_mov_b32_e32 v171, v226
	v_mov_b32_e32 v151, v153
	v_pk_add_f32 v[198:199], v[198:199], v[200:201]
	v_pk_add_f32 v[150:151], v[150:151], v[170:171]
	v_add_co_u32_e32 v160, vcc, s16, v160
	v_pk_add_f32 v[150:151], v[150:151], v[198:199]
	s_nop 0
	v_addc_co_u32_e32 v161, vcc, 0, v161, vcc
	v_add_f32_e32 v150, v150, v151
	ds_bpermute_b32 v151, v174, v150
	v_mov_b32_e32 v164, v169
	v_mov_b32_e32 v191, 0
	v_mov_b32_e32 v218, 0
	v_mov_b32_e32 v219, 0
	s_waitcnt lgkmcnt(0)
	v_add_f32_e32 v150, v150, v151
	ds_bpermute_b32 v151, v175, v150
	v_mov_b32_e32 v220, 0
	v_mov_b32_e32 v221, 0
	v_mov_b32_e32 v222, 0
	s_add_u32 s4, s4, s34
	s_waitcnt lgkmcnt(0)
	v_add_f32_e32 v150, v150, v151
	ds_bpermute_b32 v151, v176, v150
	s_addc_u32 s5, s5, s35
	v_lshl_add_u64 v[172:173], s[28:29], 0, v[132:133]
	v_lshl_add_u64 v[130:131], v[130:131], 0, s[6:7]
	v_lshl_add_u64 v[132:133], v[132:133], 0, s[10:11]
	s_waitcnt lgkmcnt(0)
	v_add_f32_e32 v150, v150, v151
	ds_bpermute_b32 v151, v177, v150
	s_cmpk_lt_i32 s4, 0x2000
	s_waitcnt lgkmcnt(0)
	v_add_f32_e32 v150, v150, v151
	ds_bpermute_b32 v151, v178, v150
	s_waitcnt lgkmcnt(0)
	v_add_f32_e32 v150, v150, v151
	ds_bpermute_b32 v151, v179, v150
	s_waitcnt lgkmcnt(0)
	v_add_f32_e32 v150, v150, v151
	v_fmamk_f32 v150, v150, 0x3a000000, v190
	v_mul_f32_e32 v151, 0x4b800000, v150
	v_cmp_gt_f32_e32 vcc, s15, v150
	s_nop 1
	v_cndmask_b32_e32 v150, v150, v151, vcc
	v_rsq_f32_e32 v150, v150
	s_nop 0
	v_mul_f32_e32 v151, 0x45800000, v150
	v_cndmask_b32_e32 v150, v150, v151, vcc
	v_pk_mul_f32 v[134:135], v[150:151], v[134:135] op_sel_hi:[0,1]
	v_pk_mul_f32 v[136:137], v[150:151], v[136:137] op_sel_hi:[0,1]
	v_pk_mul_f32 v[152:153], v[150:151], v[206:207] op_sel_hi:[0,1]
	v_pk_mul_f32 v[138:139], v[150:151], v[138:139] op_sel_hi:[0,1]
	v_pk_mul_f32 v[140:141], v[150:151], v[140:141] op_sel_hi:[0,1]
	v_pk_mul_f32 v[142:143], v[150:151], v[142:143] op_sel_hi:[0,1]
	v_pk_mul_f32 v[146:147], v[146:147], v[150:151] op_sel_hi:[1,0]
	v_pk_mul_f32 v[144:145], v[144:145], v[150:151] op_sel_hi:[1,0]
	v_pk_mul_f32 v[166:167], v[150:151], v[208:209] op_sel_hi:[0,1]
	v_pk_mul_f32 v[148:149], v[150:151], v[148:149] op_sel_hi:[0,1]
	v_pk_mul_f32 v[168:169], v[150:151], v[210:211] op_sel_hi:[0,1]
	v_pk_fma_f32 v[66:67], v[78:79], v[136:137], v[66:67]
	v_pk_fma_f32 v[64:65], v[76:77], v[134:135], v[64:65]
	v_pk_fma_f32 v[70:71], v[74:75], v[138:139], v[70:71]
	v_pk_fma_f32 v[68:69], v[72:73], v[152:153], v[68:69]
	v_pk_mul_f32 v[154:155], v[150:151], v[154:155] op_sel_hi:[0,1]
	v_pk_mul_f32 v[156:157], v[150:151], v[156:157] op_sel_hi:[0,1]
	v_pk_fma_f32 v[72:73], v[94:95], v[142:143], v[86:87]
	v_pk_fma_f32 v[74:75], v[92:93], v[140:141], v[84:85]
	v_pk_fma_f32 v[76:77], v[90:91], v[144:145], v[82:83]
	v_pk_fma_f32 v[78:79], v[88:89], v[146:147], v[80:81]
	v_pk_fma_f32 v[80:81], v[98:99], v[148:149], v[102:103]
	v_pk_fma_f32 v[82:83], v[96:97], v[166:167], v[100:101]
	v_pk_fma_f32 v[86:87], v[108:109], v[168:169], v[104:105]
	v_cvt_pk_bf16_f32 v96, v64, v65
	v_cvt_pk_bf16_f32 v97, v66, v67
	v_cvt_pk_bf16_f32 v98, v68, v69
	v_cvt_pk_bf16_f32 v99, v70, v71
	v_mov_b32_e32 v102, v65
	v_mov_b32_e32 v103, v69
	v_mov_b32_e32 v104, v66
	v_mov_b32_e32 v105, v70
	v_pk_fma_f32 v[84:85], v[110:111], v[154:155], v[106:107]
	s_waitcnt vmcnt(5)
	v_pk_fma_f32 v[90:91], v[112:113], v[156:157], v[120:121]
	v_mov_b32_e32 v100, v64
	v_mov_b32_e32 v101, v68
	v_mov_b32_e32 v106, v67
	v_mov_b32_e32 v107, v71
	v_pk_mul_f32 v[110:111], v[72:73], v[72:73]
	v_pk_mul_f32 v[112:113], v[74:75], v[74:75]
	global_store_dwordx2 v[160:161], v[96:97], off sc1
	global_store_dwordx2 v[160:161], v[98:99], off offset:512 sc1
	v_pk_mul_f32 v[96:97], v[102:103], v[102:103]
	v_pk_mul_f32 v[98:99], v[104:105], v[104:105]
	v_pk_mul_f32 v[158:159], v[150:151], v[158:159] op_sel_hi:[0,1]
	v_pk_mul_f32 v[164:165], v[164:165], v[150:151] op_sel_hi:[1,0]
	v_pk_mul_f32 v[150:151], v[162:163], v[150:151] op_sel_hi:[1,0]
	v_pk_mov_b32 v[102:103], v[112:113], v[110:111] op_sel:[1,0]
	v_mov_b32_e32 v113, v111
	v_pk_fma_f32 v[96:97], v[100:101], v[100:101], v[96:97]
	v_pk_fma_f32 v[98:99], v[106:107], v[106:107], v[98:99]
	s_waitcnt vmcnt(4)
	v_pk_fma_f32 v[92:93], v[126:127], v[150:151], v[118:119]
	v_pk_fma_f32 v[94:95], v[124:125], v[164:165], v[116:117]
	v_cvt_pk_bf16_f32 v108, v74, v75
	v_cvt_pk_bf16_f32 v109, v72, v73
	v_mul_f32_e32 v116, v78, v78
	v_mul_f32_e32 v118, v76, v76
	v_pk_add_f32 v[100:101], v[112:113], v[102:103]
	v_pk_add_f32 v[96:97], v[96:97], v[98:99]
	global_store_dwordx2 v[160:161], v[108:109], off offset:1024 sc1
	v_pk_fma_f32 v[104:105], v[78:79], v[78:79], v[116:117] op_sel_hi:[1,1,0]
	v_pk_fma_f32 v[108:109], v[76:77], v[76:77], v[118:119] op_sel_hi:[1,1,0]
	v_pk_add_f32 v[98:99], v[100:101], v[100:101] op_sel_hi:[0,1]
	v_pk_add_f32 v[96:97], v[96:97], v[96:97] op_sel_hi:[0,1]
	v_pk_mul_f32 v[124:125], v[84:85], v[84:85]
	v_pk_mul_f32 v[126:127], v[86:87], v[86:87]
	v_mul_f32_e32 v104, v82, v82
	v_mul_f32_e32 v108, v83, v83
	v_mul_f32_e32 v98, v81, v81
	v_mul_f32_e32 v96, v80, v80
	v_pk_fma_f32 v[88:89], v[114:115], v[158:159], v[122:123]
	v_pk_mov_b32 v[110:111], v[126:127], v[124:125] op_sel:[1,0]
	v_mov_b32_e32 v127, v125
	v_pk_add_f32 v[100:101], v[104:105], v[108:109]
	v_pk_add_f32 v[96:97], v[98:99], v[96:97]
	v_cvt_pk_bf16_f32 v114, v78, v79
	v_cvt_pk_bf16_f32 v115, v76, v77
	v_mul_f32_e32 v136, v90, v90
	v_mul_f32_e32 v138, v88, v88
	v_pk_add_f32 v[102:103], v[126:127], v[110:111]
	v_pk_add_f32 v[96:97], v[100:101], v[96:97]
	global_store_dwordx2 v[160:161], v[114:115], off offset:1536 sc1
	v_pk_fma_f32 v[114:115], v[90:91], v[90:91], v[136:137] op_sel_hi:[1,1,0]
	v_pk_fma_f32 v[116:117], v[88:89], v[88:89], v[138:139] op_sel_hi:[1,1,0]
	v_pk_add_f32 v[102:103], v[102:103], v[102:103] op_sel_hi:[0,1]
	v_pk_add_f32 v[96:97], v[96:97], v[96:97] op_sel_hi:[0,1]
	v_mul_f32_e32 v114, v94, v94
	v_mul_f32_e32 v116, v95, v95
	v_mul_f32_e32 v102, v93, v93
	v_mul_f32_e32 v96, v92, v92
	v_pk_add_f32 v[104:105], v[114:115], v[116:117]
	v_pk_add_f32 v[96:97], v[102:103], v[96:97]
	v_cvt_pk_bf16_f32 v120, v82, v83
	v_pk_add_f32 v[96:97], v[104:105], v[96:97]
	v_cvt_pk_bf16_f32 v122, v86, v87
	v_add_f32_e32 v96, v96, v97
	ds_bpermute_b32 v97, v174, v96
	v_cvt_pk_bf16_f32 v134, v90, v91
	v_cvt_pk_bf16_f32 v140, v94, v95
	v_cvt_pk_bf16_f32 v121, v80, v81
	v_cvt_pk_bf16_f32 v123, v84, v85
	s_waitcnt lgkmcnt(0)
	v_add_f32_e32 v96, v96, v97
	ds_bpermute_b32 v97, v175, v96
	v_cvt_pk_bf16_f32 v135, v88, v89
	v_cvt_pk_bf16_f32 v141, v92, v93
	global_store_dwordx2 v[160:161], v[120:121], off offset:2048 sc1
	global_store_dwordx2 v[160:161], v[122:123], off offset:2560 sc1
	global_store_dwordx2 v[160:161], v[134:135], off offset:3072 sc1
	s_waitcnt lgkmcnt(0)
	v_add_f32_e32 v96, v96, v97
	ds_bpermute_b32 v97, v176, v96
	global_store_dwordx2 v[160:161], v[140:141], off offset:3584 sc1
	s_waitcnt lgkmcnt(0)
	v_add_f32_e32 v96, v96, v97
	ds_bpermute_b32 v97, v177, v96
	s_waitcnt lgkmcnt(0)
	v_add_f32_e32 v96, v96, v97
	ds_bpermute_b32 v97, v178, v96
	s_waitcnt lgkmcnt(0)
	v_add_f32_e32 v96, v96, v97
	ds_bpermute_b32 v97, v179, v96
	s_waitcnt lgkmcnt(0)
	v_add_f32_e32 v96, v96, v97
	v_fmamk_f32 v96, v96, 0x3a000000, v190
	v_mul_f32_e32 v97, 0x4b800000, v96
	v_cmp_gt_f32_e32 vcc, s15, v96
	s_nop 1
	v_cndmask_b32_e32 v96, v96, v97, vcc
	v_rsq_f32_e32 v96, v96
	s_nop 0
	v_mul_f32_e32 v97, 0x45800000, v96
	v_cndmask_b32_e32 v96, v96, v97, vcc
	v_pk_mul_f32 v[64:65], v[64:65], v[96:97] op_sel_hi:[1,0]
	v_pk_mul_f32 v[66:67], v[66:67], v[96:97] op_sel_hi:[1,0]
	v_pk_mul_f32 v[68:69], v[68:69], v[96:97] op_sel_hi:[1,0]
	v_pk_fma_f32 v[0:1], v[0:1], v[64:65], v[4:5]
	v_pk_mul_f32 v[70:71], v[70:71], v[96:97] op_sel_hi:[1,0]
	v_pk_mul_f32 v[74:75], v[74:75], v[96:97] op_sel_hi:[1,0]
	v_pk_fma_f32 v[2:3], v[2:3], v[66:67], v[6:7]
	v_pk_fma_f32 v[6:7], v[8:9], v[68:69], v[12:13]
	v_cvt_pk_fp8_f32 v191, v0, v1
	v_pk_mul_f32 v[78:79], v[78:79], v[96:97] op_sel_hi:[1,0]
	v_pk_fma_f32 v[4:5], v[10:11], v[70:71], v[14:15]
	v_pk_fma_f32 v[10:11], v[16:17], v[74:75], v[20:21]
	v_cvt_pk_fp8_f32 v203, v6, v7
	v_pk_mul_f32 v[72:73], v[72:73], v[96:97] op_sel_hi:[1,0]
	v_pk_mul_f32 v[76:77], v[76:77], v[96:97] op_sel_hi:[1,0]
	v_pk_mul_f32 v[82:83], v[82:83], v[96:97] op_sel_hi:[1,0]
	v_pk_mul_f32 v[86:87], v[86:87], v[96:97] op_sel_hi:[1,0]
	v_pk_mul_f32 v[90:91], v[90:91], v[96:97] op_sel_hi:[1,0]
	v_pk_mul_f32 v[94:95], v[94:95], v[96:97] op_sel_hi:[1,0]
	v_pk_fma_f32 v[14:15], v[24:25], v[78:79], v[28:29]
	v_cvt_pk_fp8_f32 v205, v10, v11
	v_pk_fma_f32 v[8:9], v[18:19], v[72:73], v[22:23]
	v_pk_fma_f32 v[12:13], v[26:27], v[76:77], v[30:31]
	v_pk_fma_f32 v[18:19], v[36:37], v[82:83], v[32:33]
	v_pk_fma_f32 v[22:23], v[40:41], v[86:87], v[44:45]
	v_pk_fma_f32 v[26:27], v[52:53], v[90:91], v[48:49]
	s_waitcnt vmcnt(8)
	v_pk_fma_f32 v[30:31], v[56:57], v[94:95], v[60:61]
	v_cvt_pk_fp8_f32 v218, v14, v15
	v_cvt_pk_fp8_f32 v219, v18, v19
	v_cvt_pk_fp8_f32 v220, v22, v23
	v_cvt_pk_fp8_f32 v221, v26, v27
	v_cvt_pk_fp8_f32 v222, v30, v31
	v_cvt_pk_fp8_f32 v191, v2, v3 op_sel:[0,0,1]
	v_cvt_pk_fp8_f32 v203, v4, v5 op_sel:[0,0,1]
	v_pk_mul_f32 v[80:81], v[80:81], v[96:97] op_sel_hi:[1,0]
	v_pk_mul_f32 v[84:85], v[84:85], v[96:97] op_sel_hi:[1,0]
	v_pk_mul_f32 v[88:89], v[88:89], v[96:97] op_sel_hi:[1,0]
	v_pk_mul_f32 v[92:93], v[92:93], v[96:97] op_sel_hi:[1,0]
	v_cvt_pk_fp8_f32 v205, v8, v9 op_sel:[0,0,1]
	v_pk_fma_f32 v[16:17], v[38:39], v[80:81], v[34:35]
	v_pk_fma_f32 v[20:21], v[42:43], v[84:85], v[46:47]
	v_pk_fma_f32 v[24:25], v[54:55], v[88:89], v[50:51]
	v_pk_fma_f32 v[28:29], v[58:59], v[92:93], v[62:63]
	v_cvt_pk_fp8_f32 v218, v12, v13 op_sel:[0,0,1]
	v_cvt_pk_fp8_f32 v219, v16, v17 op_sel:[0,0,1]
	v_cvt_pk_fp8_f32 v220, v20, v21 op_sel:[0,0,1]
	v_cvt_pk_fp8_f32 v221, v24, v25 op_sel:[0,0,1]
	v_cvt_pk_fp8_f32 v222, v28, v29 op_sel:[0,0,1]
	global_store_dword v[172:173], v191, off offset:-1024 sc1
	global_store_dword v[172:173], v203, off offset:-768 sc1
	global_store_dword v[172:173], v205, off offset:-512 sc1
	global_store_dword v[172:173], v218, off offset:-256 sc1
	global_store_dword v[172:173], v219, off sc1
	global_store_dword v[172:173], v220, off offset:256 sc1
	global_store_dword v[172:173], v221, off offset:512 sc1
	global_store_dword v[172:173], v222, off offset:768 sc1
	s_cbranch_scc1 .LBB0_997
